# adds SG step-3 load batching and next-token H-row LDS-DMA prefetch (issued before LN finish) in PEER gather
# baseline (speedup 1.0000x reference)
.LBB0_370:
	s_or_b64 exec, exec, s[6:7]
	s_waitcnt lgkmcnt(0)
	v_and_b32_e32 v2, 0x7f, v167
	v_or_b32_e32 v0, s8, v2
	s_movk_i32 s0, 0x1600
	v_mul_lo_u32 v0, v0, s0
	v_mov_b32_e32 v1, v16
	v_mov_b64_e32 v[42:43], s[4:5]
	v_lshl_add_u64 v[0:1], v[0:1], 1, s[4:5]
	s_lshl_b32 s4, s35, 7
	v_readlane_b32 s10, v255, 26
	s_and_b32 s4, s4, 0x180
	v_readlane_b32 s11, v255, 27
	s_lshl_b32 s82, s4, 1
	v_and_b32_e32 v12, 0xffffffe0, v17
	s_lshl_b64 s[6:7], s[10:11], 2
	s_lshl_b32 s5, s4, 2
	v_lshl_add_u64 v[0:1], v[0:1], 0, s[82:83]
	v_ashrrev_i32_e32 v13, 31, v12
	s_add_u32 s6, s38, s6
	v_lshl_add_u64 v[0:1], v[12:13], 1, v[0:1]
	s_mov_b64 s[0:1], 0x1c00
	s_addc_u32 s7, s39, s7
	v_lshl_add_u64 v[8:9], v[0:1], 0, s[0:1]
	s_add_u32 s6, s6, s5
	v_add_co_u32_e32 v0, vcc, s85, v0
	v_lshl_add_u32 v37, v2, 3, 0
	s_addc_u32 s7, s7, 0
	v_addc_co_u32_e32 v1, vcc, 0, v1, vcc
	s_barrier
	v_lshlrev_b32_e32 v36, 1, v2
	ds_read_b64 v[44:45], v37 offset:34816
	v_lshl_add_u64 v[14:15], v[12:13], 2, s[6:7]
	v_mul_i32_i24_e32 v13, -6, v2
	global_load_dwordx4 v[18:21], v[0:1], off offset:3072
	s_nop 0
	global_load_dwordx4 v[0:3], v[8:9], off offset:48
	global_load_dwordx4 v[4:7], v[8:9], off offset:32
	s_nop 0
	global_load_dwordx4 v[8:11], v[8:9], off offset:16
	s_mov_b32 s5, 0x12724000
	s_mov_b64 s[6:7], 0x12724980
	v_lshl_add_u64 v[22:23], v[14:15], 0, s[6:7]
	s_mov_b64 s[6:7], 0x12726980
	v_lshl_add_u64 v[38:39], v[14:15], 0, s[6:7]
	s_or_b32 s4, s10, s4
	v_bfe_u32 v47, v167, 4, 2
	v_and_b32_e32 v46, 15, v167
	s_waitcnt vmcnt(3)
	v_lshlrev_b32_e32 v24, 16, v18
	s_waitcnt lgkmcnt(0)
	v_sub_f32_e32 v24, v24, v44
	v_mul_f32_e32 v40, v45, v24
	v_add_co_u32_e32 v24, vcc, s5, v14
	s_mov_b32 s5, 0x12726000
	s_nop 0
	v_addc_co_u32_e32 v25, vcc, 0, v15, vcc
	v_add_co_u32_e32 v14, vcc, s5, v14
	global_load_dwordx4 v[24:27], v[24:25], off offset:2432
	s_nop 0
	global_load_dwordx4 v[28:31], v[22:23], off offset:48
	global_load_dwordx4 v[32:35], v[22:23], off offset:32
	global_load_dwordx4 v[50:53], v[22:23], off offset:16
	v_addc_co_u32_e32 v15, vcc, 0, v15, vcc
	global_load_dwordx4 v[54:57], v[14:15], off offset:2432
	global_load_dwordx4 v[58:61], v[38:39], off offset:48
	global_load_dwordx4 v[62:65], v[38:39], off offset:32
	global_load_dwordx4 v[66:69], v[38:39], off offset:16
	v_and_b32_e32 v15, 0xffff0000, v18
	v_sub_f32_e32 v15, v15, v44
	v_mul_f32_e32 v15, v45, v15
	s_mov_b32 s5, s11
	s_lshl_b64 s[6:7], s[4:5], 8
	s_add_u32 s6, s38, s6
	s_addc_u32 s7, s39, s7
	s_lshl_b64 s[4:5], s[4:5], 2
	s_add_u32 s4, s38, s4
	s_addc_u32 s5, s39, s5
	s_add_u32 s4, s4, 0x12728980
	s_addc_u32 s5, s5, 0
	s_waitcnt vmcnt(3)
	v_fma_f32 v14, v24, v40, v54
	v_fma_f32 v15, v25, v15, v55
	v_cvt_pk_bf16_f32 v14, v14, s0
	v_cvt_pk_bf16_f32 v15, v15, s0
	s_movk_i32 s0, 0x110
	v_mul_lo_u32 v12, v12, s0
	v_add3_u32 v48, v37, v13, v12
	v_add3_u32 v49, 0, v12, v36
	v_lshlrev_b32_e32 v12, 16, v19
	v_sub_f32_e32 v12, v12, v44
	v_and_b32_e32 v13, 0xffff0000, v19
	v_mul_f32_e32 v12, v45, v12
	v_sub_f32_e32 v13, v13, v44
	v_fma_f32 v12, v12, v26, v56
	v_mul_f32_e32 v13, v45, v13
	v_fmac_f32_e32 v57, v13, v27
	v_cvt_pk_bf16_f32 v12, v12, s0
	ds_write_b16 v48, v14
	ds_write_b16 v49, v15 offset:272
	v_cvt_pk_bf16_f32 v13, v57, s0
	ds_write_b16 v48, v12 offset:544
	ds_write_b16 v49, v13 offset:816
	v_lshlrev_b32_e32 v12, 16, v20
	v_sub_f32_e32 v12, v12, v44
	v_and_b32_e32 v13, 0xffff0000, v20
	v_mul_f32_e32 v12, v45, v12
	v_sub_f32_e32 v13, v13, v44
	s_waitcnt vmcnt(0)
	v_fma_f32 v12, v12, v50, v66
	v_mul_f32_e32 v13, v45, v13
	v_fma_f32 v13, v13, v51, v67
	v_cvt_pk_bf16_f32 v12, v12, s0
	v_cvt_pk_bf16_f32 v13, v13, s0
	ds_write_b16 v48, v12 offset:1088
	ds_write_b16 v49, v13 offset:1360
	v_lshlrev_b32_e32 v12, 16, v21
	v_sub_f32_e32 v12, v12, v44
	v_and_b32_e32 v13, 0xffff0000, v21
	v_mul_f32_e32 v12, v45, v12
	v_sub_f32_e32 v13, v13, v44
	v_fma_f32 v12, v12, v52, v68
	v_mul_f32_e32 v13, v45, v13
	v_fmac_f32_e32 v69, v13, v53
	v_cvt_pk_bf16_f32 v12, v12, s0
	v_cvt_pk_bf16_f32 v13, v69, s0
	ds_write_b16 v48, v12 offset:1632
	ds_write_b16 v49, v13 offset:1904
	v_lshlrev_b32_e32 v12, 16, v8
	v_and_b32_e32 v8, 0xffff0000, v8
	v_sub_f32_e32 v12, v12, v44
	v_sub_f32_e32 v8, v8, v44
	v_mul_f32_e32 v12, v45, v12
	v_mul_f32_e32 v8, v45, v8
	v_fma_f32 v12, v32, v12, v62
	v_fma_f32 v8, v33, v8, v63
	v_cvt_pk_bf16_f32 v12, v12, s0
	v_cvt_pk_bf16_f32 v8, v8, s0
	ds_write_b16 v48, v12 offset:2176
	ds_write_b16 v49, v8 offset:2448
	v_lshlrev_b32_e32 v8, 16, v9
	v_sub_f32_e32 v8, v8, v44
	v_and_b32_e32 v9, 0xffff0000, v9
	v_mul_f32_e32 v8, v45, v8
	v_sub_f32_e32 v9, v9, v44
	v_fma_f32 v8, v8, v34, v64
	v_mul_f32_e32 v9, v45, v9
	v_fmac_f32_e32 v65, v9, v35
	v_cvt_pk_bf16_f32 v8, v8, s0
	v_cvt_pk_bf16_f32 v9, v65, s0
	ds_write_b16 v48, v8 offset:2720
	ds_write_b16 v49, v9 offset:2992
	v_lshlrev_b32_e32 v8, 16, v10
	v_sub_f32_e32 v8, v8, v44
	v_and_b32_e32 v9, 0xffff0000, v10
	v_mul_f32_e32 v8, v45, v8
	v_sub_f32_e32 v9, v9, v44
	v_fma_f32 v8, v8, v28, v58
	v_mul_f32_e32 v9, v45, v9
	v_fma_f32 v9, v9, v29, v59
	v_cvt_pk_bf16_f32 v8, v8, s0
	v_cvt_pk_bf16_f32 v9, v9, s0
	ds_write_b16 v48, v8 offset:3264
	ds_write_b16 v49, v9 offset:3536
	v_lshlrev_b32_e32 v8, 16, v11
	v_sub_f32_e32 v8, v8, v44
	v_and_b32_e32 v9, 0xffff0000, v11
	v_mul_f32_e32 v8, v45, v8
	v_sub_f32_e32 v9, v9, v44
	v_fma_f32 v8, v8, v30, v60
	v_mul_f32_e32 v9, v45, v9
	v_fmac_f32_e32 v61, v9, v31
	v_cvt_pk_bf16_f32 v8, v8, s0
	v_cvt_pk_bf16_f32 v9, v61, s0
	ds_write_b16 v48, v8 offset:3808
	ds_write_b16 v49, v9 offset:4080
	v_lshlrev_b32_e32 v8, 16, v4
	v_sub_f32_e32 v8, v8, v44
	v_mul_f32_e32 v50, v45, v8
	global_load_dwordx4 v[8:11], v[22:23], off offset:112
	global_load_dwordx4 v[12:15], v[22:23], off offset:96
	global_load_dwordx4 v[18:21], v[22:23], off offset:80
	global_load_dwordx4 v[34:37], v[22:23], off offset:64
	s_nop 0
	global_load_dwordx4 v[22:25], v[38:39], off offset:112
	global_load_dwordx4 v[26:29], v[38:39], off offset:96
	global_load_dwordx4 v[30:33], v[38:39], off offset:80
	s_nop 0
	global_load_dwordx4 v[38:41], v[38:39], off offset:64
	v_and_b32_e32 v4, 0xffff0000, v4
	v_sub_f32_e32 v4, v4, v44
	v_mul_f32_e32 v4, v45, v4
	s_waitcnt vmcnt(0)
	v_fma_f32 v34, v34, v50, v38
	v_fma_f32 v4, v35, v4, v39
	v_cvt_pk_bf16_f32 v34, v34, s0
	v_cvt_pk_bf16_f32 v4, v4, s0
	ds_write_b16 v48, v34 offset:4352
	ds_write_b16 v49, v4 offset:4624
	v_lshlrev_b32_e32 v4, 16, v5
	v_sub_f32_e32 v4, v4, v44
	v_and_b32_e32 v5, 0xffff0000, v5
	v_mul_f32_e32 v4, v45, v4
	v_sub_f32_e32 v5, v5, v44
	v_fma_f32 v4, v4, v36, v40
	v_mul_f32_e32 v5, v45, v5
	v_fmac_f32_e32 v41, v5, v37
	v_cvt_pk_bf16_f32 v4, v4, s0
	v_cvt_pk_bf16_f32 v5, v41, s0
	ds_write_b16 v48, v4 offset:4896
	ds_write_b16 v49, v5 offset:5168
	v_lshlrev_b32_e32 v4, 16, v6
	v_sub_f32_e32 v4, v4, v44
	v_and_b32_e32 v5, 0xffff0000, v6
	v_mul_f32_e32 v4, v45, v4
	v_sub_f32_e32 v5, v5, v44
	v_fma_f32 v4, v4, v18, v30
	v_mul_f32_e32 v5, v45, v5
	v_fma_f32 v5, v5, v19, v31
	v_cvt_pk_bf16_f32 v4, v4, s0
	v_cvt_pk_bf16_f32 v5, v5, s0
	ds_write_b16 v48, v4 offset:5440
	ds_write_b16 v49, v5 offset:5712
	v_lshlrev_b32_e32 v4, 16, v7
	v_sub_f32_e32 v4, v4, v44
	v_and_b32_e32 v5, 0xffff0000, v7
	v_mul_f32_e32 v4, v45, v4
	v_sub_f32_e32 v5, v5, v44
	v_fma_f32 v4, v4, v20, v32
	v_mul_f32_e32 v5, v45, v5
	v_fmac_f32_e32 v33, v5, v21
	v_cvt_pk_bf16_f32 v4, v4, s0
	v_cvt_pk_bf16_f32 v5, v33, s0
	ds_write_b16 v48, v4 offset:5984
	ds_write_b16 v49, v5 offset:6256
	v_lshlrev_b32_e32 v4, 16, v0
	v_and_b32_e32 v0, 0xffff0000, v0
	v_sub_f32_e32 v4, v4, v44
	v_sub_f32_e32 v0, v0, v44
	v_mul_f32_e32 v4, v45, v4
	v_mul_f32_e32 v0, v45, v0
	v_fma_f32 v4, v12, v4, v26
	v_fma_f32 v0, v13, v0, v27
	v_cvt_pk_bf16_f32 v4, v4, s0
	v_cvt_pk_bf16_f32 v0, v0, s0
	ds_write_b16 v48, v4 offset:6528
	ds_write_b16 v49, v0 offset:6800
	v_lshlrev_b32_e32 v0, 16, v1
	v_sub_f32_e32 v0, v0, v44
	v_and_b32_e32 v1, 0xffff0000, v1
	v_mul_f32_e32 v0, v45, v0
	v_sub_f32_e32 v1, v1, v44
	v_fma_f32 v0, v0, v14, v28
	v_mul_f32_e32 v1, v45, v1
	v_fmac_f32_e32 v29, v1, v15
	v_cvt_pk_bf16_f32 v0, v0, s0
	v_cvt_pk_bf16_f32 v1, v29, s0
	ds_write_b16 v48, v0 offset:7072
	ds_write_b16 v49, v1 offset:7344
	v_lshlrev_b32_e32 v0, 16, v2
	v_sub_f32_e32 v0, v0, v44
	v_and_b32_e32 v1, 0xffff0000, v2
	v_mul_f32_e32 v0, v45, v0
	v_sub_f32_e32 v1, v1, v44
	v_fma_f32 v0, v0, v8, v22
	v_mul_f32_e32 v1, v45, v1
	v_fma_f32 v1, v1, v9, v23
	v_cvt_pk_bf16_f32 v0, v0, s0
	v_cvt_pk_bf16_f32 v1, v1, s0
	ds_write_b16 v48, v0 offset:7616
	ds_write_b16 v49, v1 offset:7888
	v_lshlrev_b32_e32 v0, 16, v3
	v_sub_f32_e32 v0, v0, v44
	v_and_b32_e32 v1, 0xffff0000, v3
	v_mul_f32_e32 v0, v45, v0
	v_sub_f32_e32 v1, v1, v44
	v_fma_f32 v0, v0, v10, v24
	v_mul_f32_e32 v1, v45, v1
	v_fmac_f32_e32 v25, v1, v11
	v_cvt_pk_bf16_f32 v0, v0, s0
	v_cvt_pk_bf16_f32 v1, v25, s0
	ds_write_b16 v48, v0 offset:8160
	ds_write_b16 v49, v1 offset:8432
	v_bfi_b32 v0, -16, v17, v167
	v_and_b32_e32 v20, -16, v17
	v_mul_lo_u32 v0, v0, s0
	v_lshlrev_b32_e32 v18, 4, v47
	v_mov_b32_e32 v19, v16
	v_add3_u32 v0, 0, v0, v18
	v_lshl_add_u64 v[18:19], s[6:7], 0, v[18:19]
	v_lshl_or_b32 v22, v47, 2, v20
	v_lshlrev_b32_e32 v20, 8, v46
	v_mov_b32_e32 v21, v16
	v_lshl_add_u64 v[24:25], v[18:19], 0, v[20:21]
	s_mov_b64 s[6:7], 0x12604000
	v_lshl_add_u64 v[30:31], v[24:25], 0, s[6:7]
	s_mov_b32 s6, 0x12605000
	v_add_co_u32_e32 v32, vcc, s6, v24
	s_waitcnt lgkmcnt(0)
	s_nop 0
	v_addc_co_u32_e32 v33, vcc, 0, v25, vcc
	s_barrier
	ds_read_b128 v[12:15], v0
	ds_read_b128 v[8:11], v0 offset:64
	ds_read_b128 v[4:7], v0 offset:128
	ds_read_b128 v[0:3], v0 offset:192
	v_ashrrev_i32_e32 v23, 31, v22
	v_lshlrev_b64 v[22:23], 1, v[22:23]
	v_lshlrev_b32_e32 v17, 2, v46
	s_mov_b32 s98, 0x2000
	s_mov_b32 s99, 0
	v_lshl_add_u64 v[48:49], v[32:33], 0, s[98:99]
	v_lshl_add_u64 v[50:51], v[48:49], 0, s[98:99]
	v_lshl_add_u64 v[52:53], v[50:51], 0, s[98:99]
	global_load_dwordx4 v[72:75], v[32:33], off offset:-4096
	global_load_dwordx4 v[76:79], v[32:33], off offset:-4032
	global_load_dwordx4 v[80:83], v[32:33], off offset:-3968
	global_load_dwordx4 v[84:87], v[32:33], off offset:-3904
	global_load_dwordx4 v[88:91], v[32:33], off
	global_load_dwordx4 v[92:95], v[32:33], off offset:64
	global_load_dwordx4 v[96:99], v[32:33], off offset:128
	global_load_dwordx4 v[100:103], v[32:33], off offset:192
	global_load_dwordx4 v[104:107], v[48:49], off offset:-4096
	global_load_dwordx4 v[108:111], v[48:49], off offset:-4032
	global_load_dwordx4 v[112:115], v[48:49], off offset:-3968
	global_load_dwordx4 v[116:119], v[48:49], off offset:-3904
	global_load_dwordx4 v[120:123], v[48:49], off
	global_load_dwordx4 v[124:127], v[48:49], off offset:64
	global_load_dwordx4 v[128:131], v[48:49], off offset:128
	global_load_dwordx4 v[132:135], v[48:49], off offset:192
	global_load_dwordx4 v[136:139], v[50:51], off offset:-4096
	global_load_dwordx4 v[140:143], v[50:51], off offset:-4032
	global_load_dwordx4 v[144:147], v[50:51], off offset:-3968
	global_load_dwordx4 v[152:155], v[50:51], off offset:-3904
	global_load_dwordx4 v[156:159], v[50:51], off
	global_load_dwordx4 v[160:163], v[50:51], off offset:64
	global_load_dwordx4 v[172:175], v[50:51], off offset:128
	global_load_dwordx4 v[176:179], v[50:51], off offset:192
	global_load_dwordx4 v[180:183], v[52:53], off offset:-4096
	global_load_dwordx4 v[196:199], v[52:53], off offset:-4032
	global_load_dwordx4 v[200:203], v[52:53], off offset:-3968
	global_load_dwordx4 v[204:207], v[52:53], off offset:-3904
	global_load_dwordx4 v[208:211], v[52:53], off
	global_load_dwordx4 v[216:219], v[52:53], off offset:64
	global_load_dwordx4 v[220:223], v[52:53], off offset:128
	global_load_dwordx4 v[224:227], v[52:53], off offset:192
	global_load_dword v228, v17, s[4:5]
	global_load_dword v229, v17, s[4:5] offset:64
	global_load_dword v230, v17, s[4:5] offset:128
	global_load_dword v231, v17, s[4:5] offset:192
	global_load_dword v232, v17, s[4:5] offset:256
	global_load_dword v233, v17, s[4:5] offset:320
	global_load_dword v234, v17, s[4:5] offset:384
	global_load_dword v235, v17, s[4:5] offset:448
	v_or_b32_e32 v28, s8, v46
	v_mad_u64_u32 v[54:55], s[6:7], v28, s59, v[42:43]
	v_lshl_add_u64 v[54:55], v[54:55], 0, s[82:83]
	v_lshl_add_u64 v[54:55], v[54:55], 0, v[22:23]
	s_mov_b32 s100, 0x1000
	s_mov_b32 s101, 0
	v_lshl_add_u64 v[54:55], v[54:55], 0, s[100:101]
	s_mov_b32 s100, 0x2c000
	global_load_dwordx2 v[236:237], v[54:55], off offset:2048
	v_lshl_add_u64 v[54:55], v[54:55], 0, s[100:101]
	global_load_dwordx2 v[238:239], v[54:55], off offset:2048
	v_lshl_add_u64 v[54:55], v[54:55], 0, s[100:101]
	global_load_dwordx2 v[240:241], v[54:55], off offset:2048
	v_lshl_add_u64 v[54:55], v[54:55], 0, s[100:101]
	global_load_dwordx2 v[242:243], v[54:55], off offset:2048
	v_lshl_add_u64 v[54:55], v[54:55], 0, s[100:101]
	global_load_dwordx2 v[244:245], v[54:55], off offset:2048
	v_lshl_add_u64 v[54:55], v[54:55], 0, s[100:101]
	global_load_dwordx2 v[246:247], v[54:55], off offset:2048
	v_lshl_add_u64 v[54:55], v[54:55], 0, s[100:101]
	global_load_dwordx2 v[248:249], v[54:55], off offset:2048
	v_lshl_add_u64 v[54:55], v[54:55], 0, s[100:101]
	global_load_dwordx2 v[250:251], v[54:55], off offset:2048
	v_mov_b32_e32 v29, v16
	v_lshlrev_b64 v[56:57], 12, v[28:29]
	v_lshl_add_u64 v[56:57], s[38:39], 0, v[56:57]
	v_lshl_add_u64 v[56:57], v[56:57], 0, s[82:83]
	v_lshl_add_u64 v[56:57], v[56:57], 0, v[22:23]
	s_mov_b32 s0, 0x26b4b000
	v_add_co_u32_e32 v56, vcc, s0, v56
	s_nop 1
	v_addc_co_u32_e32 v57, vcc, 0, v57, vcc
	s_mov_b32 s98, 0x10000
	s_waitcnt vmcnt(44) lgkmcnt(0)
	v_mfma_f32_16x16x32_bf16 v[72:75], v[12:15], v[72:75], 0
	v_mfma_f32_16x16x32_bf16 v[72:75], v[8:11], v[76:79], v[72:75]
	v_mfma_f32_16x16x32_bf16 v[72:75], v[4:7], v[80:83], v[72:75]
	v_mfma_f32_16x16x32_bf16 v[72:75], v[0:3], v[84:87], v[72:75]
	s_waitcnt vmcnt(40)
	v_mfma_f32_16x16x32_bf16 v[88:91], v[12:15], v[88:91], 0
	v_mfma_f32_16x16x32_bf16 v[88:91], v[8:11], v[92:95], v[88:91]
	v_mfma_f32_16x16x32_bf16 v[88:91], v[4:7], v[96:99], v[88:91]
	v_mfma_f32_16x16x32_bf16 v[88:91], v[0:3], v[100:103], v[88:91]
	s_waitcnt vmcnt(36)
	v_mfma_f32_16x16x32_bf16 v[104:107], v[12:15], v[104:107], 0
	v_mfma_f32_16x16x32_bf16 v[104:107], v[8:11], v[108:111], v[104:107]
	v_mfma_f32_16x16x32_bf16 v[104:107], v[4:7], v[112:115], v[104:107]
	v_mfma_f32_16x16x32_bf16 v[104:107], v[0:3], v[116:119], v[104:107]
	s_waitcnt vmcnt(32)
	v_mfma_f32_16x16x32_bf16 v[120:123], v[12:15], v[120:123], 0
	v_mfma_f32_16x16x32_bf16 v[120:123], v[8:11], v[124:127], v[120:123]
	v_mfma_f32_16x16x32_bf16 v[120:123], v[4:7], v[128:131], v[120:123]
	v_mfma_f32_16x16x32_bf16 v[120:123], v[0:3], v[132:135], v[120:123]
	s_waitcnt vmcnt(28)
	v_mfma_f32_16x16x32_bf16 v[136:139], v[12:15], v[136:139], 0
	v_mfma_f32_16x16x32_bf16 v[136:139], v[8:11], v[140:143], v[136:139]
	v_mfma_f32_16x16x32_bf16 v[136:139], v[4:7], v[144:147], v[136:139]
	v_mfma_f32_16x16x32_bf16 v[136:139], v[0:3], v[152:155], v[136:139]
	s_waitcnt vmcnt(24)
	v_mfma_f32_16x16x32_bf16 v[156:159], v[12:15], v[156:159], 0
	v_mfma_f32_16x16x32_bf16 v[156:159], v[8:11], v[160:163], v[156:159]
	v_mfma_f32_16x16x32_bf16 v[156:159], v[4:7], v[172:175], v[156:159]
	v_mfma_f32_16x16x32_bf16 v[156:159], v[0:3], v[176:179], v[156:159]
	s_waitcnt vmcnt(20)
	v_mfma_f32_16x16x32_bf16 v[180:183], v[12:15], v[180:183], 0
	v_mfma_f32_16x16x32_bf16 v[180:183], v[8:11], v[196:199], v[180:183]
	v_mfma_f32_16x16x32_bf16 v[180:183], v[4:7], v[200:203], v[180:183]
	v_mfma_f32_16x16x32_bf16 v[180:183], v[0:3], v[204:207], v[180:183]
	s_waitcnt vmcnt(16)
	v_mfma_f32_16x16x32_bf16 v[208:211], v[12:15], v[208:211], 0
	v_mfma_f32_16x16x32_bf16 v[208:211], v[8:11], v[216:219], v[208:211]
	v_mfma_f32_16x16x32_bf16 v[208:211], v[4:7], v[220:223], v[208:211]
	v_mfma_f32_16x16x32_bf16 v[208:211], v[0:3], v[224:227], v[208:211]
	s_waitcnt vmcnt(0)
	v_pk_add_f32 v[72:73], v[72:73], v[228:229] op_sel_hi:[1,0]
	v_pk_add_f32 v[74:75], v[74:75], v[228:229] op_sel_hi:[1,0]
	v_lshlrev_b32_e32 v58, 16, v236
	v_and_b32_e32 v59, 0xffff0000, v236
	v_lshlrev_b32_e32 v60, 16, v237
	v_and_b32_e32 v61, 0xffff0000, v237
	v_pk_mul_f32 v[72:73], v[72:73], v[58:59]
	v_pk_mul_f32 v[74:75], v[74:75], v[60:61]
	v_cvt_pk_bf16_f32 v72, v72, v73
	v_cvt_pk_bf16_f32 v73, v74, v75
	global_store_dwordx2 v[56:57], v[72:73], off offset:2560
	v_lshl_add_u64 v[56:57], v[56:57], 0, s[98:99]
	v_pk_add_f32 v[88:89], v[88:89], v[228:229] op_sel:[0,1] op_sel_hi:[1,1]
	v_pk_add_f32 v[90:91], v[90:91], v[228:229] op_sel:[0,1] op_sel_hi:[1,1]
	v_lshlrev_b32_e32 v58, 16, v238
	v_and_b32_e32 v59, 0xffff0000, v238
	v_lshlrev_b32_e32 v60, 16, v239
	v_and_b32_e32 v61, 0xffff0000, v239
	v_pk_mul_f32 v[88:89], v[88:89], v[58:59]
	v_pk_mul_f32 v[90:91], v[90:91], v[60:61]
	v_cvt_pk_bf16_f32 v88, v88, v89
	v_cvt_pk_bf16_f32 v89, v90, v91
	global_store_dwordx2 v[56:57], v[88:89], off offset:2560
	v_lshl_add_u64 v[56:57], v[56:57], 0, s[98:99]
	v_pk_add_f32 v[104:105], v[104:105], v[230:231] op_sel_hi:[1,0]
	v_pk_add_f32 v[106:107], v[106:107], v[230:231] op_sel_hi:[1,0]
	v_lshlrev_b32_e32 v58, 16, v240
	v_and_b32_e32 v59, 0xffff0000, v240
	v_lshlrev_b32_e32 v60, 16, v241
	v_and_b32_e32 v61, 0xffff0000, v241
	v_pk_mul_f32 v[104:105], v[104:105], v[58:59]
	v_pk_mul_f32 v[106:107], v[106:107], v[60:61]
	v_cvt_pk_bf16_f32 v104, v104, v105
	v_cvt_pk_bf16_f32 v105, v106, v107
	global_store_dwordx2 v[56:57], v[104:105], off offset:2560
	v_lshl_add_u64 v[56:57], v[56:57], 0, s[98:99]
	v_pk_add_f32 v[120:121], v[120:121], v[230:231] op_sel:[0,1] op_sel_hi:[1,1]
	v_pk_add_f32 v[122:123], v[122:123], v[230:231] op_sel:[0,1] op_sel_hi:[1,1]
	v_lshlrev_b32_e32 v58, 16, v242
	v_and_b32_e32 v59, 0xffff0000, v242
	v_lshlrev_b32_e32 v60, 16, v243
	v_and_b32_e32 v61, 0xffff0000, v243
	v_pk_mul_f32 v[120:121], v[120:121], v[58:59]
	v_pk_mul_f32 v[122:123], v[122:123], v[60:61]
	v_cvt_pk_bf16_f32 v120, v120, v121
	v_cvt_pk_bf16_f32 v121, v122, v123
	global_store_dwordx2 v[56:57], v[120:121], off offset:2560
	v_lshl_add_u64 v[56:57], v[56:57], 0, s[98:99]
	v_pk_add_f32 v[136:137], v[136:137], v[232:233] op_sel_hi:[1,0]
	v_pk_add_f32 v[138:139], v[138:139], v[232:233] op_sel_hi:[1,0]
	v_lshlrev_b32_e32 v58, 16, v244
	v_and_b32_e32 v59, 0xffff0000, v244
	v_lshlrev_b32_e32 v60, 16, v245
	v_and_b32_e32 v61, 0xffff0000, v245
	v_pk_mul_f32 v[136:137], v[136:137], v[58:59]
	v_pk_mul_f32 v[138:139], v[138:139], v[60:61]
	v_cvt_pk_bf16_f32 v136, v136, v137
	v_cvt_pk_bf16_f32 v137, v138, v139
	global_store_dwordx2 v[56:57], v[136:137], off offset:2560
	v_lshl_add_u64 v[56:57], v[56:57], 0, s[98:99]
	v_pk_add_f32 v[156:157], v[156:157], v[232:233] op_sel:[0,1] op_sel_hi:[1,1]
	v_pk_add_f32 v[158:159], v[158:159], v[232:233] op_sel:[0,1] op_sel_hi:[1,1]
	v_lshlrev_b32_e32 v58, 16, v246
	v_and_b32_e32 v59, 0xffff0000, v246
	v_lshlrev_b32_e32 v60, 16, v247
	v_and_b32_e32 v61, 0xffff0000, v247
	v_pk_mul_f32 v[156:157], v[156:157], v[58:59]
	v_pk_mul_f32 v[158:159], v[158:159], v[60:61]
	v_cvt_pk_bf16_f32 v156, v156, v157
	v_cvt_pk_bf16_f32 v157, v158, v159
	global_store_dwordx2 v[56:57], v[156:157], off offset:2560
	v_lshl_add_u64 v[56:57], v[56:57], 0, s[98:99]
	v_pk_add_f32 v[180:181], v[180:181], v[234:235] op_sel_hi:[1,0]
	v_pk_add_f32 v[182:183], v[182:183], v[234:235] op_sel_hi:[1,0]
	v_lshlrev_b32_e32 v58, 16, v248
	v_and_b32_e32 v59, 0xffff0000, v248
	v_lshlrev_b32_e32 v60, 16, v249
	v_and_b32_e32 v61, 0xffff0000, v249
	v_pk_mul_f32 v[180:181], v[180:181], v[58:59]
	v_pk_mul_f32 v[182:183], v[182:183], v[60:61]
	v_cvt_pk_bf16_f32 v180, v180, v181
	v_cvt_pk_bf16_f32 v181, v182, v183
	global_store_dwordx2 v[56:57], v[180:181], off offset:2560
	v_lshl_add_u64 v[56:57], v[56:57], 0, s[98:99]
	v_pk_add_f32 v[208:209], v[208:209], v[234:235] op_sel:[0,1] op_sel_hi:[1,1]
	v_pk_add_f32 v[210:211], v[210:211], v[234:235] op_sel:[0,1] op_sel_hi:[1,1]
	v_lshlrev_b32_e32 v58, 16, v250
	v_and_b32_e32 v59, 0xffff0000, v250
	v_lshlrev_b32_e32 v60, 16, v251
	v_and_b32_e32 v61, 0xffff0000, v251
	v_pk_mul_f32 v[208:209], v[208:209], v[58:59]
	v_pk_mul_f32 v[210:211], v[210:211], v[60:61]
	v_cvt_pk_bf16_f32 v208, v208, v209
	v_cvt_pk_bf16_f32 v209, v210, v211
	global_store_dwordx2 v[56:57], v[208:209], off offset:2560
	s_barrier

.Lpeer_extra:
	s_setprio 0
	s_lshl_b32 s62, s49, 14
	s_sub_i32 s63, s52, s80
	s_lshl_b32 s63, s63, 4
	s_mov_b32 s61, 4
	s_mov_b32 s101, 15
	s_mov_b32 s100, 0
	s_mov_b64 s[34:35], 0
	v_add_u32_e32 v223, 8, v215
	s_branch .LBB0_732

.LBB0_728:
	s_add_i32 s52, s12, s80
	s_cmpk_lt_i32 s52, 0x300
	s_cselect_b64 s[10:11], -1, 0
	s_cmpk_gt_i32 s52, 0x2ff
	s_cselect_b64 s[26:27], -1, 0
	s_and_b64 s[28:29], s[6:7], s[10:11]
	s_lshl_b32 s53, s49, 14
	s_xor_b64 s[28:29], s[28:29], -1
	s_and_saveexec_b64 s[30:31], s[28:29]
	s_xor_b64 s[28:29], exec, s[30:31]
	s_cbranch_execz .LBB0_803
	s_and_saveexec_b64 s[30:31], s[8:9]
	s_cbranch_execz .LBB0_802
	s_and_b64 s[10:11], s[10:11], exec
	s_cselect_b32 s61, 4, 8
	s_cselect_b32 s101, 11, 15
	s_add_i32 s62, s53, 0
	s_lshl_b32 s63, s12, 4
	s_mov_b32 s100, 0
	s_mov_b64 s[34:35], 0
	v_mov_b32_e32 v223, v215
	s_branch .LBB0_732

.LBB0_732:
	s_mov_b64 s[36:37], s[16:17]
	v_mov_b32_e32 v17, v214
	v_lshl_add_u32 v12, v223, 9, s62
	v_add_u32_e32 v180, s63, v223
	v_ashrrev_i32_e32 v181, 31, v180
	v_lshl_add_u32 v0, v17, 2, v12
	ds_read2st64_b32 v[150:151], v0 offset0:160 offset1:161
	v_lshlrev_b64 v[0:1], 12, v[180:181]
	v_lshl_add_u64 v[0:1], s[36:37], 0, v[0:1]
	s_mov_b64 s[10:11], 0x1b74b200
	v_lshl_add_u64 v[178:179], v[0:1], 0, s[10:11]
	v_lshlrev_b32_e32 v0, 5, v17
	v_ashrrev_i32_e32 v1, 31, v0
	v_lshl_add_u64 v[0:1], v[0:1], 1, v[178:179]
	s_cmp_eq_u32 s100, 1
	s_cbranch_scc1 .Lhpf_lds
	global_load_dwordx4 v[2:5], v[0:1], off offset:48
	global_load_dwordx4 v[6:9], v[0:1], off offset:32
	global_load_dwordx4 v[18:21], v[0:1], off offset:16
	global_load_dwordx4 v[22:25], v[0:1], off
	s_branch .Lhpf_done
.Lhpf_lds:
	s_lshl_b32 s98, s90, 12
	s_add_i32 s98, s98, 0x1b000
	v_lshl_add_u32 v246, v214, 4, s98
	s_waitcnt vmcnt(0)
	ds_read_b128 v[22:25], v246
	ds_read_b128 v[18:21], v246 offset:1024
	ds_read_b128 v[6:9], v246 offset:2048
	ds_read_b128 v[2:5], v246 offset:3072
	s_waitcnt lgkmcnt(0)
.Lhpf_done:
	v_mov_b32_e32 v0, v16
	v_lshl_add_u32 v10, v17, 4, v216
	v_and_b32_e32 v158, 15, v17
	s_add_u32 s10, s36, s20
	s_addc_u32 s11, s37, s21
	s_add_u32 s12, s10, 0x9a04000
	s_addc_u32 s13, s11, 0
	v_and_b32_e32 v152, -16, v17
	v_ashrrev_i32_e32 v153, 31, v152
	v_lshlrev_b32_e32 v224, 3, v17
	v_and_b32_e32 v154, 3, v17
	s_mov_b64 s[0:1], 0xda04000
	s_waitcnt vmcnt(3)
	v_lshlrev_b32_e32 v53, 16, v2
	v_and_b32_e32 v55, 0xffff0000, v2
	v_lshlrev_b32_e32 v57, 16, v3
	s_waitcnt vmcnt(0)
	v_lshlrev_b32_e32 v1, 16, v22
	v_and_b32_e32 v13, 0xffff0000, v22
	v_mul_f32_e32 v11, 0x3e800000, v1
	v_mul_f32_e32 v14, 0x3e800000, v13
	v_lshlrev_b32_e32 v15, 16, v23
	v_and_b32_e32 v23, 0xffff0000, v23
	v_mul_f32_e32 v22, 0x3e800000, v15
	v_mul_f32_e32 v26, 0x3e800000, v23
	v_lshlrev_b32_e32 v27, 16, v24
	v_and_b32_e32 v24, 0xffff0000, v24
	v_cvt_scalef32_pk_fp4_f32 v0, v11, v14, 1.0
	v_mul_f32_e32 v28, 0x3e800000, v27
	v_mul_f32_e32 v29, 0x3e800000, v24
	v_lshlrev_b32_e32 v30, 16, v25
	v_and_b32_e32 v25, 0xffff0000, v25
	v_cvt_scalef32_pk_fp4_f32 v0, v22, v26, 1.0 op_sel:[0,0,1,0]
	v_mul_f32_e32 v31, 0x3e800000, v30
	v_mul_f32_e32 v32, 0x3e800000, v25
	v_cvt_scalef32_pk_fp4_f32 v0, v28, v29, 1.0 op_sel:[0,0,0,1]
	v_lshlrev_b32_e32 v11, 16, v18
	v_cvt_scalef32_pk_fp4_f32 v0, v31, v32, 1.0 op_sel:[0,0,1,1]
	v_and_b32_e32 v18, 0xffff0000, v18
	v_and_b32_e32 v59, 0xffff0000, v3
	v_cvt_scalef32_pk_f32_fp4 v[2:3], v0, 1.0
	v_mul_f32_e32 v14, 0x3e800000, v11
	v_mul_f32_e32 v22, 0x3e800000, v18
	v_lshlrev_b32_e32 v26, 16, v19
	v_and_b32_e32 v19, 0xffff0000, v19
	v_fma_f32 v69, v1, s87, -v2
	v_mov_b32_e32 v1, v16
	v_mul_f32_e32 v28, 0x3e800000, v26
	v_mul_f32_e32 v29, 0x3e800000, v19
	v_lshlrev_b32_e32 v31, 16, v20
	v_and_b32_e32 v20, 0xffff0000, v20
	v_cvt_scalef32_pk_fp4_f32 v1, v14, v22, 1.0
	v_mul_f32_e32 v32, 0x3e800000, v31
	v_mul_f32_e32 v33, 0x3e800000, v20
	v_lshlrev_b32_e32 v34, 16, v21
	v_and_b32_e32 v21, 0xffff0000, v21
	v_cvt_scalef32_pk_fp4_f32 v1, v28, v29, 1.0 op_sel:[0,0,1,0]
	v_mul_f32_e32 v35, 0x3e800000, v34
	v_mul_f32_e32 v36, 0x3e800000, v21
	v_cvt_scalef32_pk_fp4_f32 v1, v32, v33, 1.0 op_sel:[0,0,0,1]
	v_lshlrev_b32_e32 v37, 16, v6
	v_cvt_scalef32_pk_fp4_f32 v1, v35, v36, 1.0 op_sel:[0,0,1,1]
	v_and_b32_e32 v39, 0xffff0000, v6
	v_fma_f32 v13, v13, s87, -v3
	v_cvt_scalef32_pk_f32_fp4 v[2:3], v1, 1.0
	v_mul_f32_e32 v38, 0x3e800000, v37
	v_mul_f32_e32 v40, 0x3e800000, v39
	v_lshlrev_b32_e32 v41, 16, v7
	v_and_b32_e32 v43, 0xffff0000, v7
	v_mul_f32_e32 v54, 0x3e800000, v53
	v_mul_f32_e32 v56, 0x3e800000, v55
	v_fma_f32 v11, v11, s87, -v2
	v_fma_f32 v18, v18, s87, -v3
	v_mov_b32_e32 v2, v16
	v_mov_b32_e32 v3, v16
	v_mul_f32_e32 v42, 0x3e800000, v41
	v_mul_f32_e32 v44, 0x3e800000, v43
	v_lshlrev_b32_e32 v45, 16, v8
	v_and_b32_e32 v47, 0xffff0000, v8
	v_mul_f32_e32 v58, 0x3e800000, v57
	v_mul_f32_e32 v60, 0x3e800000, v59
	v_lshlrev_b32_e32 v61, 16, v4
	v_and_b32_e32 v63, 0xffff0000, v4
	v_cvt_scalef32_pk_fp4_f32 v2, v38, v40, 1.0
	v_cvt_scalef32_pk_fp4_f32 v3, v54, v56, 1.0
	v_mul_f32_e32 v46, 0x3e800000, v45
	v_mul_f32_e32 v48, 0x3e800000, v47
	v_lshlrev_b32_e32 v49, 16, v9
	v_and_b32_e32 v51, 0xffff0000, v9
	v_mul_f32_e32 v62, 0x3e800000, v61
	v_mul_f32_e32 v64, 0x3e800000, v63
	v_lshlrev_b32_e32 v65, 16, v5
	v_and_b32_e32 v67, 0xffff0000, v5
	v_cvt_scalef32_pk_fp4_f32 v2, v42, v44, 1.0 op_sel:[0,0,1,0]
	v_cvt_scalef32_pk_fp4_f32 v3, v58, v60, 1.0 op_sel:[0,0,1,0]
	v_mul_f32_e32 v50, 0x3e800000, v49
	v_mul_f32_e32 v52, 0x3e800000, v51
	v_mul_f32_e32 v66, 0x3e800000, v65
	v_mul_f32_e32 v68, 0x3e800000, v67
	v_cvt_scalef32_pk_fp4_f32 v2, v46, v48, 1.0 op_sel:[0,0,0,1]
	v_cvt_scalef32_pk_fp4_f32 v3, v62, v64, 1.0 op_sel:[0,0,0,1]
	v_cvt_scalef32_pk_f32_fp4 v[4:5], v0, 1.0 op_sel:[1,0,0]
	v_cvt_scalef32_pk_fp4_f32 v2, v50, v52, 1.0 op_sel:[0,0,1,1]
	v_cvt_scalef32_pk_fp4_f32 v3, v66, v68, 1.0 op_sel:[0,0,1,1]
	v_cvt_scalef32_pk_f32_fp4 v[6:7], v0, 1.0 op_sel:[0,1,0]
	v_cvt_scalef32_pk_f32_fp4 v[8:9], v0, 1.0 op_sel:[1,1,0]
	v_mul_f32_e32 v70, 4.0, v69
	v_mul_f32_e32 v71, 4.0, v13
	v_fma_f32 v72, v15, s87, -v4
	v_fma_f32 v23, v23, s87, -v5
	v_cvt_scalef32_pk_f32_fp4 v[4:5], v1, 1.0 op_sel:[1,0,0]
	ds_write_b128 v10, v[0:3]
	v_mov_b32_e32 v0, v16
	v_mul_f32_e32 v73, 4.0, v72
	v_mul_f32_e32 v74, 4.0, v23
	v_fma_f32 v27, v27, s87, -v6
	v_fma_f32 v24, v24, s87, -v7
	v_fma_f32 v30, v30, s87, -v8
	v_fma_f32 v25, v25, s87, -v9
	v_cvt_scalef32_pk_f32_fp4 v[6:7], v1, 1.0 op_sel:[0,1,0]
	v_cvt_scalef32_pk_f32_fp4 v[8:9], v1, 1.0 op_sel:[1,1,0]
	v_mul_f32_e32 v22, 4.0, v11
	v_mul_f32_e32 v28, 4.0, v18
	v_fma_f32 v26, v26, s87, -v4
	v_fma_f32 v19, v19, s87, -v5
	v_cvt_scalef32_pk_fp4_f32 v0, v70, v71, 1.0
	v_mov_b32_e32 v1, v16
	v_mul_f32_e32 v75, 4.0, v27
	v_mul_f32_e32 v76, 4.0, v24
	v_mul_f32_e32 v29, 4.0, v26
	v_mul_f32_e32 v32, 4.0, v19
	v_fma_f32 v31, v31, s87, -v6
	v_fma_f32 v20, v20, s87, -v7
	v_cvt_scalef32_pk_fp4_f32 v0, v73, v74, 1.0 op_sel:[0,0,1,0]
	v_cvt_scalef32_pk_fp4_f32 v1, v22, v28, 1.0
	v_mul_f32_e32 v77, 4.0, v30
	v_mul_f32_e32 v78, 4.0, v25
	v_mul_f32_e32 v33, 4.0, v31
	v_mul_f32_e32 v35, 4.0, v20
	v_fma_f32 v34, v34, s87, -v8
	v_fma_f32 v21, v21, s87, -v9
	v_cvt_scalef32_pk_fp4_f32 v0, v75, v76, 1.0 op_sel:[0,0,0,1]
	v_cvt_scalef32_pk_fp4_f32 v1, v29, v32, 1.0 op_sel:[0,0,1,0]
	v_mul_f32_e32 v36, 4.0, v34
	v_mul_f32_e32 v79, 4.0, v21
	v_cvt_scalef32_pk_f32_fp4 v[4:5], v2, 1.0
	v_cvt_scalef32_pk_f32_fp4 v[6:7], v2, 1.0 op_sel:[1,0,0]
	v_cvt_scalef32_pk_f32_fp4 v[8:9], v2, 1.0 op_sel:[0,1,0]
	v_cvt_scalef32_pk_f32_fp4 v[14:15], v2, 1.0 op_sel:[1,1,0]
	v_cvt_scalef32_pk_fp4_f32 v0, v77, v78, 1.0 op_sel:[0,0,1,1]
	v_cvt_scalef32_pk_fp4_f32 v1, v33, v35, 1.0 op_sel:[0,0,0,1]
	v_fma_f32 v37, v37, s87, -v4
	v_fma_f32 v39, v39, s87, -v5
	v_fma_f32 v41, v41, s87, -v6
	v_fma_f32 v43, v43, s87, -v7
	v_fma_f32 v45, v45, s87, -v8
	v_fma_f32 v47, v47, s87, -v9
	v_fma_f32 v49, v49, s87, -v14
	v_fma_f32 v51, v51, s87, -v15
	v_cvt_scalef32_pk_f32_fp4 v[4:5], v3, 1.0
	v_cvt_scalef32_pk_f32_fp4 v[6:7], v3, 1.0 op_sel:[1,0,0]
	v_cvt_scalef32_pk_f32_fp4 v[8:9], v3, 1.0 op_sel:[0,1,0]
	v_cvt_scalef32_pk_f32_fp4 v[14:15], v3, 1.0 op_sel:[1,1,0]
	v_cvt_scalef32_pk_f32_fp4 v[2:3], v0, 1.0
	v_cvt_scalef32_pk_fp4_f32 v1, v36, v79, 1.0 op_sel:[0,0,1,1]
	v_fma_f32 v53, v53, s87, -v4
	v_fma_f32 v55, v55, s87, -v5
	v_fma_f32 v69, v69, 4.0, -v2
	v_fma_f32 v13, v13, 4.0, -v3
	v_cvt_scalef32_pk_f32_fp4 v[2:3], v1, 1.0
	v_mul_f32_e32 v38, 4.0, v37
	v_mul_f32_e32 v40, 4.0, v39
	v_mul_f32_e32 v54, 4.0, v53
	v_mul_f32_e32 v56, 4.0, v55
	v_fma_f32 v57, v57, s87, -v6
	v_fma_f32 v59, v59, s87, -v7
	v_fma_f32 v11, v11, 4.0, -v2
	v_fma_f32 v18, v18, 4.0, -v3
	v_mov_b32_e32 v2, v16
	v_mov_b32_e32 v3, v16
	v_mul_f32_e32 v42, 4.0, v41
	v_mul_f32_e32 v44, 4.0, v43
	v_mul_f32_e32 v58, 4.0, v57
	v_mul_f32_e32 v60, 4.0, v59
	v_fma_f32 v61, v61, s87, -v8
	v_fma_f32 v63, v63, s87, -v9
	v_cvt_scalef32_pk_fp4_f32 v2, v38, v40, 1.0
	v_cvt_scalef32_pk_fp4_f32 v3, v54, v56, 1.0
	v_mul_f32_e32 v46, 4.0, v45
	v_mul_f32_e32 v48, 4.0, v47
	v_mul_f32_e32 v62, 4.0, v61
	v_mul_f32_e32 v64, 4.0, v63
	v_fma_f32 v65, v65, s87, -v14
	v_fma_f32 v67, v67, s87, -v15
	v_cvt_scalef32_pk_fp4_f32 v2, v42, v44, 1.0 op_sel:[0,0,1,0]
	v_cvt_scalef32_pk_fp4_f32 v3, v58, v60, 1.0 op_sel:[0,0,1,0]
	v_mul_f32_e32 v50, 4.0, v49
	v_mul_f32_e32 v52, 4.0, v51
	v_mul_f32_e32 v66, 4.0, v65
	v_mul_f32_e32 v68, 4.0, v67
	v_cvt_scalef32_pk_fp4_f32 v2, v46, v48, 1.0 op_sel:[0,0,0,1]
	v_cvt_scalef32_pk_fp4_f32 v3, v62, v64, 1.0 op_sel:[0,0,0,1]
	v_cvt_scalef32_pk_f32_fp4 v[4:5], v0, 1.0 op_sel:[1,0,0]
	v_cvt_scalef32_pk_fp4_f32 v2, v50, v52, 1.0 op_sel:[0,0,1,1]
	v_cvt_scalef32_pk_fp4_f32 v3, v66, v68, 1.0 op_sel:[0,0,1,1]
	v_cvt_scalef32_pk_f32_fp4 v[6:7], v0, 1.0 op_sel:[0,1,0]
	v_cvt_scalef32_pk_f32_fp4 v[8:9], v0, 1.0 op_sel:[1,1,0]
	v_mul_f32_e32 v70, 4.0, v69
	v_mul_f32_e32 v71, 4.0, v13
	v_fma_f32 v72, v72, 4.0, -v4
	v_fma_f32 v23, v23, 4.0, -v5
	ds_write_b128 v10, v[0:3] offset:1024
	v_mov_b32_e32 v0, v16
	v_mul_f32_e32 v73, 4.0, v72
	v_mul_f32_e32 v74, 4.0, v23
	v_fma_f32 v27, v27, 4.0, -v6
	v_fma_f32 v24, v24, 4.0, -v7
	v_cvt_scalef32_pk_fp4_f32 v0, v70, v71, 1.0
	v_mul_f32_e32 v75, 4.0, v27
	v_mul_f32_e32 v76, 4.0, v24
	v_fma_f32 v30, v30, 4.0, -v8
	v_fma_f32 v25, v25, 4.0, -v9
	v_cvt_scalef32_pk_fp4_f32 v0, v73, v74, 1.0 op_sel:[0,0,1,0]
	v_mul_f32_e32 v77, 4.0, v30
	v_mul_f32_e32 v78, 4.0, v25
	v_cvt_scalef32_pk_f32_fp4 v[4:5], v1, 1.0 op_sel:[1,0,0]
	v_cvt_scalef32_pk_f32_fp4 v[6:7], v1, 1.0 op_sel:[0,1,0]
	v_cvt_scalef32_pk_f32_fp4 v[8:9], v1, 1.0 op_sel:[1,1,0]
	v_cvt_scalef32_pk_fp4_f32 v0, v75, v76, 1.0 op_sel:[0,0,0,1]
	v_fma_f32 v26, v26, 4.0, -v4
	v_fma_f32 v19, v19, 4.0, -v5
	v_fma_f32 v31, v31, 4.0, -v6
	v_fma_f32 v20, v20, 4.0, -v7
	v_fma_f32 v34, v34, 4.0, -v8
	v_fma_f32 v21, v21, 4.0, -v9
	v_cvt_scalef32_pk_f32_fp4 v[4:5], v2, 1.0
	v_cvt_scalef32_pk_f32_fp4 v[6:7], v2, 1.0 op_sel:[1,0,0]
	v_cvt_scalef32_pk_f32_fp4 v[8:9], v2, 1.0 op_sel:[0,1,0]
	v_cvt_scalef32_pk_f32_fp4 v[14:15], v2, 1.0 op_sel:[1,1,0]
	v_cvt_scalef32_pk_fp4_f32 v0, v77, v78, 1.0 op_sel:[0,0,1,1]
	v_fma_f32 v37, v37, 4.0, -v4
	v_fma_f32 v39, v39, 4.0, -v5
	v_fma_f32 v41, v41, 4.0, -v6
	v_fma_f32 v43, v43, 4.0, -v7
	v_fma_f32 v45, v45, 4.0, -v8
	v_fma_f32 v47, v47, 4.0, -v9
	v_fma_f32 v49, v49, 4.0, -v14
	v_fma_f32 v51, v51, 4.0, -v15
	v_cvt_scalef32_pk_f32_fp4 v[4:5], v3, 1.0
	v_cvt_scalef32_pk_f32_fp4 v[6:7], v3, 1.0 op_sel:[1,0,0]
	v_cvt_scalef32_pk_f32_fp4 v[8:9], v3, 1.0 op_sel:[0,1,0]
	v_cvt_scalef32_pk_f32_fp4 v[14:15], v3, 1.0 op_sel:[1,1,0]
	v_cvt_scalef32_pk_f32_fp4 v[2:3], v0, 1.0
	v_fma_f32 v1, v69, 4.0, -v2
	v_fma_f32 v53, v53, 4.0, -v4
	v_fma_f32 v55, v55, 4.0, -v5
	v_cvt_scalef32_pk_f32_fp4 v[4:5], v0, 1.0 op_sel:[1,0,0]
	v_mul_f32_e32 v69, 4.0, v1
	v_fma_f32 v1, v13, 4.0, -v3
	v_mul_f32_e32 v13, 4.0, v1
	v_fma_f32 v1, v72, 4.0, -v4
	v_fma_f32 v57, v57, 4.0, -v6
	v_fma_f32 v59, v59, 4.0, -v7
	v_cvt_scalef32_pk_f32_fp4 v[6:7], v0, 1.0 op_sel:[0,1,0]
	v_mul_f32_e32 v70, 4.0, v1
	v_fma_f32 v1, v23, 4.0, -v5
	v_mul_f32_e32 v23, 4.0, v1
	v_fma_f32 v1, v27, 4.0, -v6
	v_fma_f32 v61, v61, 4.0, -v8
	v_fma_f32 v63, v63, 4.0, -v9
	v_cvt_scalef32_pk_f32_fp4 v[8:9], v0, 1.0 op_sel:[1,1,0]
	v_mul_f32_e32 v27, 4.0, v1
	v_fma_f32 v1, v24, 4.0, -v7
	v_mul_f32_e32 v24, 4.0, v1
	v_fma_f32 v1, v30, 4.0, -v8
	v_mul_f32_e32 v30, 4.0, v1
	v_fma_f32 v1, v25, 4.0, -v9
	v_mul_f32_e32 v22, 4.0, v11
	v_mul_f32_e32 v28, 4.0, v18
	v_mul_f32_e32 v25, 4.0, v1
	v_mov_b32_e32 v1, v16
	v_mul_f32_e32 v29, 4.0, v26
	v_mul_f32_e32 v32, 4.0, v19
	v_cvt_scalef32_pk_fp4_f32 v1, v22, v28, 1.0
	v_mul_f32_e32 v33, 4.0, v31
	v_mul_f32_e32 v35, 4.0, v20
	v_cvt_scalef32_pk_fp4_f32 v1, v29, v32, 1.0 op_sel:[0,0,1,0]
	v_mul_f32_e32 v36, 4.0, v34
	v_mul_f32_e32 v79, 4.0, v21
	v_cvt_scalef32_pk_fp4_f32 v1, v33, v35, 1.0 op_sel:[0,0,0,1]
	v_mul_f32_e32 v38, 4.0, v37
	v_cvt_scalef32_pk_fp4_f32 v1, v36, v79, 1.0 op_sel:[0,0,1,1]
	v_mul_f32_e32 v40, 4.0, v39
	v_cvt_scalef32_pk_f32_fp4 v[2:3], v1, 1.0
	v_fma_f32 v2, v11, 4.0, -v2
	v_cvt_scalef32_pk_f32_fp4 v[4:5], v1, 1.0 op_sel:[1,0,0]
	v_mul_f32_e32 v11, 4.0, v2
	v_fma_f32 v2, v18, 4.0, -v3
	v_mul_f32_e32 v18, 4.0, v2
	v_fma_f32 v2, v26, 4.0, -v4
	v_cvt_scalef32_pk_f32_fp4 v[6:7], v1, 1.0 op_sel:[0,1,0]
	v_mul_f32_e32 v22, 4.0, v2
	v_fma_f32 v2, v19, 4.0, -v5
	v_mul_f32_e32 v19, 4.0, v2
	v_fma_f32 v2, v31, 4.0, -v6
	v_cvt_scalef32_pk_f32_fp4 v[8:9], v1, 1.0 op_sel:[1,1,0]
	v_mul_f32_e32 v26, 4.0, v2
	v_fma_f32 v2, v20, 4.0, -v7
	v_mul_f32_e32 v20, 4.0, v2
	v_fma_f32 v2, v34, 4.0, -v8
	v_mul_f32_e32 v28, 4.0, v2
	v_fma_f32 v2, v21, 4.0, -v9
	v_mul_f32_e32 v21, 4.0, v2
	v_mov_b32_e32 v2, v16
	v_mul_f32_e32 v42, 4.0, v41
	v_mul_f32_e32 v44, 4.0, v43
	v_cvt_scalef32_pk_fp4_f32 v2, v38, v40, 1.0
	v_mul_f32_e32 v46, 4.0, v45
	v_mul_f32_e32 v48, 4.0, v47
	v_cvt_scalef32_pk_fp4_f32 v2, v42, v44, 1.0 op_sel:[0,0,1,0]
	v_mul_f32_e32 v50, 4.0, v49
	v_mul_f32_e32 v52, 4.0, v51
	v_cvt_scalef32_pk_fp4_f32 v2, v46, v48, 1.0 op_sel:[0,0,0,1]
	v_fma_f32 v65, v65, 4.0, -v14
	v_cvt_scalef32_pk_fp4_f32 v2, v50, v52, 1.0 op_sel:[0,0,1,1]
	v_fma_f32 v67, v67, 4.0, -v15
	v_cvt_scalef32_pk_f32_fp4 v[4:5], v2, 1.0
	v_fma_f32 v3, v37, 4.0, -v4
	v_cvt_scalef32_pk_f32_fp4 v[6:7], v2, 1.0 op_sel:[1,0,0]
	v_mul_f32_e32 v29, 4.0, v3
	v_fma_f32 v3, v39, 4.0, -v5
	v_mul_f32_e32 v31, 4.0, v3
	v_fma_f32 v3, v41, 4.0, -v6
	v_cvt_scalef32_pk_f32_fp4 v[8:9], v2, 1.0 op_sel:[0,1,0]
	v_mul_f32_e32 v32, 4.0, v3
	v_fma_f32 v3, v43, 4.0, -v7
	v_mul_f32_e32 v33, 4.0, v3
	v_fma_f32 v3, v45, 4.0, -v8
	v_cvt_scalef32_pk_f32_fp4 v[14:15], v2, 1.0 op_sel:[1,1,0]
	v_mul_f32_e32 v34, 4.0, v3
	v_fma_f32 v3, v47, 4.0, -v9
	v_mul_f32_e32 v35, 4.0, v3
	v_fma_f32 v3, v49, 4.0, -v14
	v_mul_f32_e32 v36, 4.0, v3
	v_fma_f32 v3, v51, 4.0, -v15
	v_mul_f32_e32 v54, 4.0, v53
	v_mul_f32_e32 v56, 4.0, v55
	v_mul_f32_e32 v37, 4.0, v3
	v_mov_b32_e32 v3, v16
	v_mul_f32_e32 v58, 4.0, v57
	v_mul_f32_e32 v60, 4.0, v59
	v_cvt_scalef32_pk_fp4_f32 v3, v54, v56, 1.0
	v_mul_f32_e32 v62, 4.0, v61
	v_mul_f32_e32 v64, 4.0, v63
	v_cvt_scalef32_pk_fp4_f32 v3, v58, v60, 1.0 op_sel:[0,0,1,0]
	v_mul_f32_e32 v66, 4.0, v65
	v_mul_f32_e32 v68, 4.0, v67
	v_cvt_scalef32_pk_fp4_f32 v3, v62, v64, 1.0 op_sel:[0,0,0,1]
	s_nop 0
	v_cvt_scalef32_pk_fp4_f32 v3, v66, v68, 1.0 op_sel:[0,0,1,1]
	ds_write_b128 v10, v[0:3] offset:2048
	v_cvt_scalef32_pk_f32_fp4 v[4:5], v3, 1.0
	v_cvt_scalef32_pk_f32_fp4 v[6:7], v3, 1.0 op_sel:[1,0,0]
	v_fma_f32 v4, v53, 4.0, -v4
	v_fma_f32 v5, v55, 4.0, -v5
	v_cvt_scalef32_pk_f32_fp4 v[8:9], v3, 1.0 op_sel:[0,1,0]
	v_cvt_scalef32_pk_f32_fp4 v[14:15], v3, 1.0 op_sel:[1,1,0]
	v_mul_f32_e32 v4, 4.0, v4
	v_mul_f32_e32 v5, 4.0, v5
	v_fma_f32 v6, v57, 4.0, -v6
	v_fma_f32 v7, v59, 4.0, -v7
	v_mov_b32_e32 v0, v16
	v_mov_b32_e32 v1, v16
	v_mov_b32_e32 v2, v16
	v_mov_b32_e32 v3, v16
	v_mul_f32_e32 v6, 4.0, v6
	v_mul_f32_e32 v7, 4.0, v7
	v_fma_f32 v8, v61, 4.0, -v8
	v_fma_f32 v9, v63, 4.0, -v9
	v_cvt_scalef32_pk_fp4_f32 v0, v69, v13, 1.0
	v_cvt_scalef32_pk_fp4_f32 v1, v11, v18, 1.0
	v_cvt_scalef32_pk_fp4_f32 v2, v29, v31, 1.0
	v_cvt_scalef32_pk_fp4_f32 v3, v4, v5, 1.0
	v_mul_f32_e32 v8, 4.0, v8
	v_mul_f32_e32 v9, 4.0, v9
	v_fma_f32 v14, v65, 4.0, -v14
	v_fma_f32 v15, v67, 4.0, -v15
	v_cvt_scalef32_pk_fp4_f32 v0, v70, v23, 1.0 op_sel:[0,0,1,0]
	v_cvt_scalef32_pk_fp4_f32 v1, v22, v19, 1.0 op_sel:[0,0,1,0]
	v_cvt_scalef32_pk_fp4_f32 v2, v32, v33, 1.0 op_sel:[0,0,1,0]
	v_cvt_scalef32_pk_fp4_f32 v3, v6, v7, 1.0 op_sel:[0,0,1,0]
	v_mul_f32_e32 v14, 4.0, v14
	v_mul_f32_e32 v15, 4.0, v15
	v_cvt_scalef32_pk_fp4_f32 v0, v27, v24, 1.0 op_sel:[0,0,0,1]
	v_cvt_scalef32_pk_fp4_f32 v1, v26, v20, 1.0 op_sel:[0,0,0,1]
	v_cvt_scalef32_pk_fp4_f32 v2, v34, v35, 1.0 op_sel:[0,0,0,1]
	v_cvt_scalef32_pk_fp4_f32 v3, v8, v9, 1.0 op_sel:[0,0,0,1]
	v_cvt_scalef32_pk_fp4_f32 v0, v30, v25, 1.0 op_sel:[0,0,1,1]
	v_cvt_scalef32_pk_fp4_f32 v1, v28, v21, 1.0 op_sel:[0,0,1,1]
	v_cvt_scalef32_pk_fp4_f32 v2, v36, v37, 1.0 op_sel:[0,0,1,1]
	v_cvt_scalef32_pk_fp4_f32 v3, v14, v15, 1.0 op_sel:[0,0,1,1]
	ds_write_b128 v10, v[0:3] offset:3072
	v_lshl_add_u32 v0, v158, 2, v12
	v_add_u32_e32 v13, 0x8000, v0
	ds_read2_b32 v[2:3], v13 offset1:16
	ds_read2_b32 v[6:7], v13 offset0:32 offset1:48
	ds_read2_b32 v[10:11], v13 offset0:64 offset1:80
	s_waitcnt lgkmcnt(2)
	v_ashrrev_i32_e32 v5, 31, v3
	v_mov_b32_e32 v4, v3
	s_waitcnt lgkmcnt(1)
	v_ashrrev_i32_e32 v9, 31, v7
	v_mov_b32_e32 v8, v7
	s_waitcnt lgkmcnt(0)
	v_ashrrev_i32_e32 v15, 31, v11
	v_mov_b32_e32 v14, v11
	v_ashrrev_i32_e32 v1, 31, v2
	v_mov_b32_e32 v0, v2
	v_lshlrev_b64 v[2:3], 10, v[4:5]
	v_ashrrev_i32_e32 v5, 31, v6
	v_mov_b32_e32 v4, v6
	v_lshlrev_b64 v[6:7], 10, v[8:9]
	v_ashrrev_i32_e32 v9, 31, v10
	v_mov_b32_e32 v8, v10
	v_lshlrev_b64 v[10:11], 10, v[14:15]
	ds_read2_b32 v[14:15], v13 offset0:96 offset1:112
	v_lshlrev_b64 v[0:1], 10, v[0:1]
	v_lshl_add_u64 v[0:1], s[12:13], 0, v[0:1]
	v_lshlrev_b64 v[4:5], 10, v[4:5]
	v_lshlrev_b64 v[8:9], 10, v[8:9]
	s_waitcnt lgkmcnt(0)
	v_ashrrev_i32_e32 v19, 31, v14
	v_mov_b32_e32 v18, v14
	v_ashrrev_i32_e32 v21, 31, v15
	v_mov_b32_e32 v20, v15
	v_lshlrev_b64 v[18:19], 10, v[18:19]
	v_lshlrev_b64 v[14:15], 10, v[20:21]
	v_lshl_add_u64 v[0:1], v[0:1], 0, v[152:153]
	v_lshl_add_u64 v[2:3], s[12:13], 0, v[2:3]
	v_lshl_add_u64 v[4:5], s[12:13], 0, v[4:5]
	v_lshl_add_u64 v[6:7], s[12:13], 0, v[6:7]
	v_lshl_add_u64 v[8:9], s[12:13], 0, v[8:9]
	v_lshl_add_u64 v[10:11], s[12:13], 0, v[10:11]
	v_lshl_add_u64 v[18:19], s[12:13], 0, v[18:19]
	v_lshl_add_u64 v[14:15], s[12:13], 0, v[14:15]
	v_lshl_add_u64 v[2:3], v[2:3], 0, v[152:153]
	v_lshl_add_u64 v[4:5], v[4:5], 0, v[152:153]
	v_lshl_add_u64 v[6:7], v[6:7], 0, v[152:153]
	v_lshl_add_u64 v[8:9], v[8:9], 0, v[152:153]
	v_lshl_add_u64 v[10:11], v[10:11], 0, v[152:153]
	v_lshl_add_u64 v[18:19], v[18:19], 0, v[152:153]
	v_lshl_add_u64 v[20:21], v[14:15], 0, v[152:153]
	global_load_dwordx4 v[22:25], v[0:1], off
	global_load_dwordx4 v[26:29], v[0:1], off offset:64
	global_load_dwordx4 v[30:33], v[2:3], off
	global_load_dwordx4 v[34:37], v[2:3], off offset:64
	global_load_dwordx4 v[38:41], v[4:5], off
	global_load_dwordx4 v[42:45], v[4:5], off offset:64
	global_load_dwordx4 v[46:49], v[6:7], off
	global_load_dwordx4 v[56:59], v[6:7], off offset:64
	global_load_dwordx4 v[60:63], v[8:9], off
	global_load_dwordx4 v[64:67], v[8:9], off offset:64
	global_load_dwordx4 v[72:75], v[10:11], off
	global_load_dwordx4 v[76:79], v[10:11], off offset:64
	global_load_dwordx4 v[80:83], v[18:19], off
	global_load_dwordx4 v[84:87], v[18:19], off offset:64
	global_load_dwordx4 v[88:91], v[20:21], off
	global_load_dwordx4 v[92:95], v[20:21], off offset:64
	v_lshlrev_b32_e32 v14, 4, v158
	v_mov_b32_e32 v15, v16
	v_and_b32_e32 v153, 0xffffff80, v224
	v_lshlrev_b32_e32 v13, 10, v154
	v_lshl_add_u64 v[14:15], s[10:11], 0, v[14:15]
	v_add_u32_e32 v225, v12, v153
	v_add3_u32 v70, v216, v13, v152
	v_lshl_add_u64 v[182:183], v[14:15], 0, s[0:1]
	ds_read_b128 v[52:55], v225 offset:32768
	ds_read_b128 v[12:15], v225 offset:32784
	global_load_dwordx4 v[96:99], v[0:1], off offset:128
	global_load_dwordx4 v[100:103], v[0:1], off offset:192
	global_load_dwordx4 v[104:107], v[2:3], off offset:128
	global_load_dwordx4 v[108:111], v[2:3], off offset:192
	global_load_dwordx4 v[112:115], v[4:5], off offset:128
	global_load_dwordx4 v[116:119], v[4:5], off offset:192
	global_load_dwordx4 v[120:123], v[6:7], off offset:128
	global_load_dwordx4 v[124:127], v[6:7], off offset:192
	ds_read_b128 v[128:131], v70 offset:64
	ds_read_b128 v[132:135], v70
	s_waitcnt vmcnt(23) lgkmcnt(0)
	v_mfma_scale_f32_16x16x128_f8f6f4 v[22:25], v[22:25], v[132:135], 0, v187, v187 op_sel_hi:[0,0,0] cbsz:4 blgp:4
	s_waitcnt vmcnt(22)
	v_mfma_scale_f32_16x16x128_f8f6f4 v[22:25], v[26:29], v[128:131], v[22:25], v187, v187 op_sel_hi:[0,0,0] cbsz:4 blgp:4
	s_waitcnt vmcnt(21)
	v_mfma_scale_f32_16x16x128_f8f6f4 v[26:29], v[30:33], v[132:135], 0, v187, v187 op_sel_hi:[0,0,0] cbsz:4 blgp:4
	s_waitcnt vmcnt(20)
	v_mfma_scale_f32_16x16x128_f8f6f4 v[26:29], v[34:37], v[128:131], v[26:29], v187, v187 op_sel_hi:[0,0,0] cbsz:4 blgp:4
	s_waitcnt vmcnt(19)
	v_mfma_scale_f32_16x16x128_f8f6f4 v[30:33], v[38:41], v[132:135], 0, v187, v187 op_sel_hi:[0,0,0] cbsz:4 blgp:4
	s_waitcnt vmcnt(17)
	v_mfma_scale_f32_16x16x128_f8f6f4 v[34:37], v[46:49], v[132:135], 0, v187, v187 op_sel_hi:[0,0,0] cbsz:4 blgp:4
	v_mfma_scale_f32_16x16x128_f8f6f4 v[30:33], v[42:45], v[128:131], v[30:33], v187, v187 op_sel_hi:[0,0,0] cbsz:4 blgp:4
	s_waitcnt vmcnt(16)
	v_mfma_scale_f32_16x16x128_f8f6f4 v[34:37], v[56:59], v[128:131], v[34:37], v187, v187 op_sel_hi:[0,0,0] cbsz:4 blgp:4
	global_load_dwordx4 v[38:41], v[8:9], off offset:128
	global_load_dwordx4 v[42:45], v[8:9], off offset:192
	global_load_dwordx4 v[46:49], v[10:11], off offset:128
	global_load_dwordx4 v[56:59], v[10:11], off offset:192
	global_load_dwordx4 v[136:139], v[18:19], off offset:128
	global_load_dwordx4 v[140:143], v[18:19], off offset:192
	global_load_dwordx4 v[144:147], v[20:21], off offset:128
	global_load_dwordx4 v[160:163], v[20:21], off offset:192
	s_waitcnt vmcnt(23)
	v_mfma_scale_f32_16x16x128_f8f6f4 v[60:63], v[60:63], v[132:135], 0, v187, v187 op_sel_hi:[0,0,0] cbsz:4 blgp:4
	s_waitcnt vmcnt(22)
	v_mfma_scale_f32_16x16x128_f8f6f4 v[60:63], v[64:67], v[128:131], v[60:63], v187, v187 op_sel_hi:[0,0,0] cbsz:4 blgp:4
	s_waitcnt vmcnt(21)
	v_mfma_scale_f32_16x16x128_f8f6f4 v[64:67], v[72:75], v[132:135], 0, v187, v187 op_sel_hi:[0,0,0] cbsz:4 blgp:4
	s_waitcnt vmcnt(20)
	v_mfma_scale_f32_16x16x128_f8f6f4 v[64:67], v[76:79], v[128:131], v[64:67], v187, v187 op_sel_hi:[0,0,0] cbsz:4 blgp:4
	s_waitcnt vmcnt(19)
	v_mfma_scale_f32_16x16x128_f8f6f4 v[72:75], v[80:83], v[132:135], 0, v187, v187 op_sel_hi:[0,0,0] cbsz:4 blgp:4
	s_waitcnt vmcnt(17)
	v_mfma_scale_f32_16x16x128_f8f6f4 v[76:79], v[88:91], v[132:135], 0, v187, v187 op_sel_hi:[0,0,0] cbsz:4 blgp:4
	v_mfma_scale_f32_16x16x128_f8f6f4 v[72:75], v[84:87], v[128:131], v[72:75], v187, v187 op_sel_hi:[0,0,0] cbsz:4 blgp:4
	s_waitcnt vmcnt(16)
	v_mfma_scale_f32_16x16x128_f8f6f4 v[76:79], v[92:95], v[128:131], v[76:79], v187, v187 op_sel_hi:[0,0,0] cbsz:4 blgp:4
	global_load_dwordx4 v[80:83], v[0:1], off offset:256
	global_load_dwordx4 v[84:87], v[0:1], off offset:320
	global_load_dwordx4 v[88:91], v[2:3], off offset:256
	global_load_dwordx4 v[92:95], v[2:3], off offset:320
	global_load_dwordx4 v[128:131], v[4:5], off offset:256
	global_load_dwordx4 v[132:135], v[4:5], off offset:320
	global_load_dwordx4 v[164:167], v[6:7], off offset:256
	global_load_dwordx4 v[168:171], v[6:7], off offset:320
	ds_read_b128 v[172:175], v70 offset:192
	ds_read_b128 v[196:199], v70 offset:128
	s_waitcnt vmcnt(23) lgkmcnt(0)
	v_mfma_scale_f32_16x16x128_f8f6f4 v[22:25], v[96:99], v[196:199], v[22:25], v187, v187 op_sel_hi:[0,0,0] cbsz:4 blgp:4
	s_waitcnt vmcnt(21)
	v_mfma_scale_f32_16x16x128_f8f6f4 v[26:29], v[104:107], v[196:199], v[26:29], v187, v187 op_sel_hi:[0,0,0] cbsz:4 blgp:4
	s_waitcnt vmcnt(19)
	v_mfma_scale_f32_16x16x128_f8f6f4 v[30:33], v[112:115], v[196:199], v[30:33], v187, v187 op_sel_hi:[0,0,0] cbsz:4 blgp:4
	s_waitcnt vmcnt(17)
	v_mfma_scale_f32_16x16x128_f8f6f4 v[34:37], v[120:123], v[196:199], v[34:37], v187, v187 op_sel_hi:[0,0,0] cbsz:4 blgp:4
	v_mfma_scale_f32_16x16x128_f8f6f4 v[22:25], v[100:103], v[172:175], v[22:25], v187, v187 op_sel_hi:[0,0,0] cbsz:4 blgp:4
	v_mfma_scale_f32_16x16x128_f8f6f4 v[26:29], v[108:111], v[172:175], v[26:29], v187, v187 op_sel_hi:[0,0,0] cbsz:4 blgp:4
	v_mfma_scale_f32_16x16x128_f8f6f4 v[30:33], v[116:119], v[172:175], v[30:33], v187, v187 op_sel_hi:[0,0,0] cbsz:4 blgp:4
	s_waitcnt vmcnt(16)
	v_mfma_scale_f32_16x16x128_f8f6f4 v[34:37], v[124:127], v[172:175], v[34:37], v187, v187 op_sel_hi:[0,0,0] cbsz:4 blgp:4
	global_load_dwordx4 v[96:99], v[8:9], off offset:256
	global_load_dwordx4 v[100:103], v[8:9], off offset:320
	global_load_dwordx4 v[104:107], v[10:11], off offset:256
	global_load_dwordx4 v[108:111], v[10:11], off offset:320
	global_load_dwordx4 v[112:115], v[18:19], off offset:256
	global_load_dwordx4 v[116:119], v[18:19], off offset:320
	global_load_dwordx4 v[120:123], v[20:21], off offset:256
	global_load_dwordx4 v[124:127], v[20:21], off offset:320
	s_waitcnt vmcnt(23)
	v_mfma_scale_f32_16x16x128_f8f6f4 v[38:41], v[38:41], v[196:199], v[60:63], v187, v187 op_sel_hi:[0,0,0] cbsz:4 blgp:4
	s_waitcnt vmcnt(22)
	v_mfma_scale_f32_16x16x128_f8f6f4 v[38:41], v[42:45], v[172:175], v[38:41], v187, v187 op_sel_hi:[0,0,0] cbsz:4 blgp:4
	s_waitcnt vmcnt(21)
	v_mfma_scale_f32_16x16x128_f8f6f4 v[42:45], v[46:49], v[196:199], v[64:67], v187, v187 op_sel_hi:[0,0,0] cbsz:4 blgp:4
	s_waitcnt vmcnt(20)
	v_mfma_scale_f32_16x16x128_f8f6f4 v[42:45], v[56:59], v[172:175], v[42:45], v187, v187 op_sel_hi:[0,0,0] cbsz:4 blgp:4
	s_waitcnt vmcnt(19)
	v_mfma_scale_f32_16x16x128_f8f6f4 v[46:49], v[136:139], v[196:199], v[72:75], v187, v187 op_sel_hi:[0,0,0] cbsz:4 blgp:4
	s_waitcnt vmcnt(17)
	v_mfma_scale_f32_16x16x128_f8f6f4 v[56:59], v[144:147], v[196:199], v[76:79], v187, v187 op_sel_hi:[0,0,0] cbsz:4 blgp:4
	v_mfma_scale_f32_16x16x128_f8f6f4 v[46:49], v[140:143], v[172:175], v[46:49], v187, v187 op_sel_hi:[0,0,0] cbsz:4 blgp:4
	s_waitcnt vmcnt(16)
	v_mfma_scale_f32_16x16x128_f8f6f4 v[56:59], v[160:163], v[172:175], v[56:59], v187, v187 op_sel_hi:[0,0,0] cbsz:4 blgp:4
	global_load_dwordx4 v[60:63], v[0:1], off offset:384
	global_load_dwordx4 v[64:67], v[0:1], off offset:448
	global_load_dwordx4 v[72:75], v[2:3], off offset:384
	global_load_dwordx4 v[76:79], v[2:3], off offset:448
	global_load_dwordx4 v[136:139], v[4:5], off offset:384
	global_load_dwordx4 v[140:143], v[4:5], off offset:448
	global_load_dwordx4 v[144:147], v[6:7], off offset:384
	global_load_dwordx4 v[160:163], v[6:7], off offset:448
	ds_read_b128 v[172:175], v70 offset:320
	ds_read_b128 v[196:199], v70 offset:256
	s_waitcnt vmcnt(23) lgkmcnt(0)
	v_mfma_scale_f32_16x16x128_f8f6f4 v[22:25], v[80:83], v[196:199], v[22:25], v187, v187 op_sel_hi:[0,0,0] cbsz:4 blgp:4
	s_waitcnt vmcnt(21)
	v_mfma_scale_f32_16x16x128_f8f6f4 v[26:29], v[88:91], v[196:199], v[26:29], v187, v187 op_sel_hi:[0,0,0] cbsz:4 blgp:4
	s_waitcnt vmcnt(19)
	v_mfma_scale_f32_16x16x128_f8f6f4 v[30:33], v[128:131], v[196:199], v[30:33], v187, v187 op_sel_hi:[0,0,0] cbsz:4 blgp:4
	s_waitcnt vmcnt(17)
	v_mfma_scale_f32_16x16x128_f8f6f4 v[34:37], v[164:167], v[196:199], v[34:37], v187, v187 op_sel_hi:[0,0,0] cbsz:4 blgp:4
	v_mfma_scale_f32_16x16x128_f8f6f4 v[22:25], v[84:87], v[172:175], v[22:25], v187, v187 op_sel_hi:[0,0,0] cbsz:4 blgp:4
	v_mfma_scale_f32_16x16x128_f8f6f4 v[26:29], v[92:95], v[172:175], v[26:29], v187, v187 op_sel_hi:[0,0,0] cbsz:4 blgp:4
	v_mfma_scale_f32_16x16x128_f8f6f4 v[30:33], v[132:135], v[172:175], v[30:33], v187, v187 op_sel_hi:[0,0,0] cbsz:4 blgp:4
	s_waitcnt vmcnt(16)
	v_mfma_scale_f32_16x16x128_f8f6f4 v[34:37], v[168:171], v[172:175], v[34:37], v187, v187 op_sel_hi:[0,0,0] cbsz:4 blgp:4
	global_load_dwordx4 v[80:83], v[8:9], off offset:384
	global_load_dwordx4 v[84:87], v[8:9], off offset:448
	global_load_dwordx4 v[88:91], v[10:11], off offset:384
	global_load_dwordx4 v[92:95], v[10:11], off offset:448
	global_load_dwordx4 v[128:131], v[18:19], off offset:384
	global_load_dwordx4 v[132:135], v[18:19], off offset:448
	global_load_dwordx4 v[164:167], v[20:21], off offset:384
	global_load_dwordx4 v[168:171], v[20:21], off offset:448
	s_waitcnt vmcnt(23)
	v_mfma_scale_f32_16x16x128_f8f6f4 v[38:41], v[96:99], v[196:199], v[38:41], v187, v187 op_sel_hi:[0,0,0] cbsz:4 blgp:4
	s_waitcnt vmcnt(21)
	v_mfma_scale_f32_16x16x128_f8f6f4 v[42:45], v[104:107], v[196:199], v[42:45], v187, v187 op_sel_hi:[0,0,0] cbsz:4 blgp:4
	s_waitcnt vmcnt(19)
	v_mfma_scale_f32_16x16x128_f8f6f4 v[46:49], v[112:115], v[196:199], v[46:49], v187, v187 op_sel_hi:[0,0,0] cbsz:4 blgp:4
	s_waitcnt vmcnt(17)
	v_mfma_scale_f32_16x16x128_f8f6f4 v[56:59], v[120:123], v[196:199], v[56:59], v187, v187 op_sel_hi:[0,0,0] cbsz:4 blgp:4
	v_mfma_scale_f32_16x16x128_f8f6f4 v[38:41], v[100:103], v[172:175], v[38:41], v187, v187 op_sel_hi:[0,0,0] cbsz:4 blgp:4
	v_mfma_scale_f32_16x16x128_f8f6f4 v[42:45], v[108:111], v[172:175], v[42:45], v187, v187 op_sel_hi:[0,0,0] cbsz:4 blgp:4
	v_mfma_scale_f32_16x16x128_f8f6f4 v[46:49], v[116:119], v[172:175], v[46:49], v187, v187 op_sel_hi:[0,0,0] cbsz:4 blgp:4
	s_waitcnt vmcnt(16)
	v_mfma_scale_f32_16x16x128_f8f6f4 v[56:59], v[124:127], v[172:175], v[56:59], v187, v187 op_sel_hi:[0,0,0] cbsz:4 blgp:4
	global_load_dwordx4 v[96:99], v[0:1], off offset:512
	global_load_dwordx4 v[100:103], v[0:1], off offset:576
	global_load_dwordx4 v[104:107], v[2:3], off offset:512
	global_load_dwordx4 v[108:111], v[2:3], off offset:576
	global_load_dwordx4 v[112:115], v[4:5], off offset:512
	global_load_dwordx4 v[116:119], v[4:5], off offset:576
	global_load_dwordx4 v[120:123], v[6:7], off offset:512
	global_load_dwordx4 v[124:127], v[6:7], off offset:576
	ds_read_b128 v[172:175], v70 offset:448
	ds_read_b128 v[196:199], v70 offset:384
	s_waitcnt vmcnt(23) lgkmcnt(0)
	v_mfma_scale_f32_16x16x128_f8f6f4 v[22:25], v[60:63], v[196:199], v[22:25], v187, v187 op_sel_hi:[0,0,0] cbsz:4 blgp:4
	s_waitcnt vmcnt(21)
	v_mfma_scale_f32_16x16x128_f8f6f4 v[26:29], v[72:75], v[196:199], v[26:29], v187, v187 op_sel_hi:[0,0,0] cbsz:4 blgp:4
	s_waitcnt vmcnt(19)
	v_mfma_scale_f32_16x16x128_f8f6f4 v[30:33], v[136:139], v[196:199], v[30:33], v187, v187 op_sel_hi:[0,0,0] cbsz:4 blgp:4
	s_waitcnt vmcnt(17)
	v_mfma_scale_f32_16x16x128_f8f6f4 v[34:37], v[144:147], v[196:199], v[34:37], v187, v187 op_sel_hi:[0,0,0] cbsz:4 blgp:4
	v_mfma_scale_f32_16x16x128_f8f6f4 v[22:25], v[64:67], v[172:175], v[22:25], v187, v187 op_sel_hi:[0,0,0] cbsz:4 blgp:4
	v_mfma_scale_f32_16x16x128_f8f6f4 v[26:29], v[76:79], v[172:175], v[26:29], v187, v187 op_sel_hi:[0,0,0] cbsz:4 blgp:4
	v_mfma_scale_f32_16x16x128_f8f6f4 v[30:33], v[140:143], v[172:175], v[30:33], v187, v187 op_sel_hi:[0,0,0] cbsz:4 blgp:4
	s_waitcnt vmcnt(16)
	v_mfma_scale_f32_16x16x128_f8f6f4 v[34:37], v[160:163], v[172:175], v[34:37], v187, v187 op_sel_hi:[0,0,0] cbsz:4 blgp:4
	global_load_dwordx4 v[60:63], v[8:9], off offset:512
	global_load_dwordx4 v[64:67], v[8:9], off offset:576
	global_load_dwordx4 v[72:75], v[10:11], off offset:512
	global_load_dwordx4 v[76:79], v[10:11], off offset:576
	global_load_dwordx4 v[136:139], v[18:19], off offset:512
	global_load_dwordx4 v[140:143], v[18:19], off offset:576
	global_load_dwordx4 v[144:147], v[20:21], off offset:512
	global_load_dwordx4 v[160:163], v[20:21], off offset:576
	s_waitcnt vmcnt(23)
	v_mfma_scale_f32_16x16x128_f8f6f4 v[38:41], v[80:83], v[196:199], v[38:41], v187, v187 op_sel_hi:[0,0,0] cbsz:4 blgp:4
	s_waitcnt vmcnt(21)
	v_mfma_scale_f32_16x16x128_f8f6f4 v[42:45], v[88:91], v[196:199], v[42:45], v187, v187 op_sel_hi:[0,0,0] cbsz:4 blgp:4
	s_waitcnt vmcnt(19)
	v_mfma_scale_f32_16x16x128_f8f6f4 v[46:49], v[128:131], v[196:199], v[46:49], v187, v187 op_sel_hi:[0,0,0] cbsz:4 blgp:4
	s_waitcnt vmcnt(17)
	v_mfma_scale_f32_16x16x128_f8f6f4 v[56:59], v[164:167], v[196:199], v[56:59], v187, v187 op_sel_hi:[0,0,0] cbsz:4 blgp:4
	v_mfma_scale_f32_16x16x128_f8f6f4 v[38:41], v[84:87], v[172:175], v[38:41], v187, v187 op_sel_hi:[0,0,0] cbsz:4 blgp:4
	v_mfma_scale_f32_16x16x128_f8f6f4 v[42:45], v[92:95], v[172:175], v[42:45], v187, v187 op_sel_hi:[0,0,0] cbsz:4 blgp:4
	v_mfma_scale_f32_16x16x128_f8f6f4 v[46:49], v[132:135], v[172:175], v[46:49], v187, v187 op_sel_hi:[0,0,0] cbsz:4 blgp:4
	s_waitcnt vmcnt(16)
	v_mfma_scale_f32_16x16x128_f8f6f4 v[56:59], v[168:171], v[172:175], v[56:59], v187, v187 op_sel_hi:[0,0,0] cbsz:4 blgp:4
	global_load_dwordx4 v[80:83], v[0:1], off offset:640
	global_load_dwordx4 v[84:87], v[0:1], off offset:704
	global_load_dwordx4 v[88:91], v[2:3], off offset:640
	global_load_dwordx4 v[92:95], v[2:3], off offset:704
	global_load_dwordx4 v[128:131], v[4:5], off offset:640
	global_load_dwordx4 v[132:135], v[4:5], off offset:704
	global_load_dwordx4 v[164:167], v[6:7], off offset:640
	global_load_dwordx4 v[168:171], v[6:7], off offset:704
	ds_read_b128 v[172:175], v70 offset:576
	ds_read_b128 v[196:199], v70 offset:512
	s_waitcnt vmcnt(23) lgkmcnt(0)
	v_mfma_scale_f32_16x16x128_f8f6f4 v[22:25], v[96:99], v[196:199], v[22:25], v187, v187 op_sel_hi:[0,0,0] cbsz:4 blgp:4
	s_waitcnt vmcnt(21)
	v_mfma_scale_f32_16x16x128_f8f6f4 v[26:29], v[104:107], v[196:199], v[26:29], v187, v187 op_sel_hi:[0,0,0] cbsz:4 blgp:4
	s_waitcnt vmcnt(19)
	v_mfma_scale_f32_16x16x128_f8f6f4 v[30:33], v[112:115], v[196:199], v[30:33], v187, v187 op_sel_hi:[0,0,0] cbsz:4 blgp:4
	s_waitcnt vmcnt(17)
	v_mfma_scale_f32_16x16x128_f8f6f4 v[34:37], v[120:123], v[196:199], v[34:37], v187, v187 op_sel_hi:[0,0,0] cbsz:4 blgp:4
	v_mfma_scale_f32_16x16x128_f8f6f4 v[22:25], v[100:103], v[172:175], v[22:25], v187, v187 op_sel_hi:[0,0,0] cbsz:4 blgp:4
	v_mfma_scale_f32_16x16x128_f8f6f4 v[26:29], v[108:111], v[172:175], v[26:29], v187, v187 op_sel_hi:[0,0,0] cbsz:4 blgp:4
	v_mfma_scale_f32_16x16x128_f8f6f4 v[30:33], v[116:119], v[172:175], v[30:33], v187, v187 op_sel_hi:[0,0,0] cbsz:4 blgp:4
	s_waitcnt vmcnt(16)
	v_mfma_scale_f32_16x16x128_f8f6f4 v[34:37], v[124:127], v[172:175], v[34:37], v187, v187 op_sel_hi:[0,0,0] cbsz:4 blgp:4
	global_load_dwordx4 v[96:99], v[8:9], off offset:640
	global_load_dwordx4 v[100:103], v[8:9], off offset:704
	global_load_dwordx4 v[104:107], v[10:11], off offset:640
	global_load_dwordx4 v[108:111], v[10:11], off offset:704
	global_load_dwordx4 v[112:115], v[18:19], off offset:640
	global_load_dwordx4 v[116:119], v[18:19], off offset:704
	global_load_dwordx4 v[120:123], v[20:21], off offset:640
	global_load_dwordx4 v[124:127], v[20:21], off offset:704
	s_waitcnt vmcnt(23)
	v_mfma_scale_f32_16x16x128_f8f6f4 v[38:41], v[60:63], v[196:199], v[38:41], v187, v187 op_sel_hi:[0,0,0] cbsz:4 blgp:4
	s_waitcnt vmcnt(21)
	v_mfma_scale_f32_16x16x128_f8f6f4 v[42:45], v[72:75], v[196:199], v[42:45], v187, v187 op_sel_hi:[0,0,0] cbsz:4 blgp:4
	s_waitcnt vmcnt(19)
	v_mfma_scale_f32_16x16x128_f8f6f4 v[46:49], v[136:139], v[196:199], v[46:49], v187, v187 op_sel_hi:[0,0,0] cbsz:4 blgp:4
	s_waitcnt vmcnt(17)
	v_mfma_scale_f32_16x16x128_f8f6f4 v[56:59], v[144:147], v[196:199], v[56:59], v187, v187 op_sel_hi:[0,0,0] cbsz:4 blgp:4
	v_mfma_scale_f32_16x16x128_f8f6f4 v[38:41], v[64:67], v[172:175], v[38:41], v187, v187 op_sel_hi:[0,0,0] cbsz:4 blgp:4
	v_mfma_scale_f32_16x16x128_f8f6f4 v[42:45], v[76:79], v[172:175], v[42:45], v187, v187 op_sel_hi:[0,0,0] cbsz:4 blgp:4
	v_mfma_scale_f32_16x16x128_f8f6f4 v[46:49], v[140:143], v[172:175], v[46:49], v187, v187 op_sel_hi:[0,0,0] cbsz:4 blgp:4
	s_waitcnt vmcnt(16)
	v_mfma_scale_f32_16x16x128_f8f6f4 v[56:59], v[160:163], v[172:175], v[56:59], v187, v187 op_sel_hi:[0,0,0] cbsz:4 blgp:4
	global_load_dwordx4 v[60:63], v[0:1], off offset:768
	global_load_dwordx4 v[64:67], v[0:1], off offset:832
	global_load_dwordx4 v[72:75], v[2:3], off offset:768
	global_load_dwordx4 v[76:79], v[2:3], off offset:832
	global_load_dwordx4 v[136:139], v[4:5], off offset:768
	global_load_dwordx4 v[140:143], v[4:5], off offset:832
	global_load_dwordx4 v[144:147], v[6:7], off offset:768
	global_load_dwordx4 v[160:163], v[6:7], off offset:832
	ds_read_b128 v[172:175], v70 offset:704
	ds_read_b128 v[196:199], v70 offset:640
	s_waitcnt vmcnt(23) lgkmcnt(0)
	v_mfma_scale_f32_16x16x128_f8f6f4 v[22:25], v[80:83], v[196:199], v[22:25], v187, v187 op_sel_hi:[0,0,0] cbsz:4 blgp:4
	s_waitcnt vmcnt(21)
	v_mfma_scale_f32_16x16x128_f8f6f4 v[26:29], v[88:91], v[196:199], v[26:29], v187, v187 op_sel_hi:[0,0,0] cbsz:4 blgp:4
	s_waitcnt vmcnt(19)
	v_mfma_scale_f32_16x16x128_f8f6f4 v[30:33], v[128:131], v[196:199], v[30:33], v187, v187 op_sel_hi:[0,0,0] cbsz:4 blgp:4
	s_waitcnt vmcnt(17)
	v_mfma_scale_f32_16x16x128_f8f6f4 v[34:37], v[164:167], v[196:199], v[34:37], v187, v187 op_sel_hi:[0,0,0] cbsz:4 blgp:4
	v_mfma_scale_f32_16x16x128_f8f6f4 v[22:25], v[84:87], v[172:175], v[22:25], v187, v187 op_sel_hi:[0,0,0] cbsz:4 blgp:4
	v_mfma_scale_f32_16x16x128_f8f6f4 v[26:29], v[92:95], v[172:175], v[26:29], v187, v187 op_sel_hi:[0,0,0] cbsz:4 blgp:4
	v_mfma_scale_f32_16x16x128_f8f6f4 v[30:33], v[132:135], v[172:175], v[30:33], v187, v187 op_sel_hi:[0,0,0] cbsz:4 blgp:4
	s_waitcnt vmcnt(16)
	v_mfma_scale_f32_16x16x128_f8f6f4 v[34:37], v[168:171], v[172:175], v[34:37], v187, v187 op_sel_hi:[0,0,0] cbsz:4 blgp:4
	global_load_dwordx4 v[80:83], v[8:9], off offset:768
	global_load_dwordx4 v[84:87], v[8:9], off offset:832
	global_load_dwordx4 v[88:91], v[10:11], off offset:768
	global_load_dwordx4 v[92:95], v[10:11], off offset:832
	global_load_dwordx4 v[128:131], v[18:19], off offset:768
	global_load_dwordx4 v[132:135], v[18:19], off offset:832
	global_load_dwordx4 v[164:167], v[20:21], off offset:768
	global_load_dwordx4 v[168:171], v[20:21], off offset:832
	s_waitcnt vmcnt(23)
	v_mfma_scale_f32_16x16x128_f8f6f4 v[38:41], v[96:99], v[196:199], v[38:41], v187, v187 op_sel_hi:[0,0,0] cbsz:4 blgp:4
	s_waitcnt vmcnt(21)
	v_mfma_scale_f32_16x16x128_f8f6f4 v[42:45], v[104:107], v[196:199], v[42:45], v187, v187 op_sel_hi:[0,0,0] cbsz:4 blgp:4
	s_waitcnt vmcnt(19)
	v_mfma_scale_f32_16x16x128_f8f6f4 v[46:49], v[112:115], v[196:199], v[46:49], v187, v187 op_sel_hi:[0,0,0] cbsz:4 blgp:4
	s_waitcnt vmcnt(17)
	v_mfma_scale_f32_16x16x128_f8f6f4 v[56:59], v[120:123], v[196:199], v[56:59], v187, v187 op_sel_hi:[0,0,0] cbsz:4 blgp:4
	v_mfma_scale_f32_16x16x128_f8f6f4 v[38:41], v[100:103], v[172:175], v[38:41], v187, v187 op_sel_hi:[0,0,0] cbsz:4 blgp:4
	v_mfma_scale_f32_16x16x128_f8f6f4 v[42:45], v[108:111], v[172:175], v[42:45], v187, v187 op_sel_hi:[0,0,0] cbsz:4 blgp:4
	v_mfma_scale_f32_16x16x128_f8f6f4 v[46:49], v[116:119], v[172:175], v[46:49], v187, v187 op_sel_hi:[0,0,0] cbsz:4 blgp:4
	s_waitcnt vmcnt(16)
	v_mfma_scale_f32_16x16x128_f8f6f4 v[56:59], v[124:127], v[172:175], v[56:59], v187, v187 op_sel_hi:[0,0,0] cbsz:4 blgp:4
	global_load_dwordx4 v[96:99], v[0:1], off offset:896
	global_load_dwordx4 v[100:103], v[0:1], off offset:960
	global_load_dwordx4 v[104:107], v[2:3], off offset:896
	global_load_dwordx4 v[108:111], v[2:3], off offset:960
	global_load_dwordx4 v[112:115], v[4:5], off offset:896
	global_load_dwordx4 v[116:119], v[4:5], off offset:960
	global_load_dwordx4 v[120:123], v[6:7], off offset:896
	global_load_dwordx4 v[124:127], v[6:7], off offset:960
	ds_read_b128 v[0:3], v70 offset:832
	ds_read_b128 v[4:7], v70 offset:768
	s_waitcnt vmcnt(23) lgkmcnt(0)
	v_mfma_scale_f32_16x16x128_f8f6f4 v[22:25], v[60:63], v[4:7], v[22:25], v187, v187 op_sel_hi:[0,0,0] cbsz:4 blgp:4
	s_waitcnt vmcnt(22)
	v_mfma_scale_f32_16x16x128_f8f6f4 v[172:175], v[64:67], v[0:3], v[22:25], v187, v187 op_sel_hi:[0,0,0] cbsz:4 blgp:4
	s_waitcnt vmcnt(21)
	v_mfma_scale_f32_16x16x128_f8f6f4 v[22:25], v[72:75], v[4:7], v[26:29], v187, v187 op_sel_hi:[0,0,0] cbsz:4 blgp:4
	s_waitcnt vmcnt(20)
	v_mfma_scale_f32_16x16x128_f8f6f4 v[72:75], v[76:79], v[0:3], v[22:25], v187, v187 op_sel_hi:[0,0,0] cbsz:4 blgp:4
	s_waitcnt vmcnt(19)
	v_mfma_scale_f32_16x16x128_f8f6f4 v[22:25], v[136:139], v[4:7], v[30:33], v187, v187 op_sel_hi:[0,0,0] cbsz:4 blgp:4
	s_waitcnt vmcnt(18)
	v_mfma_scale_f32_16x16x128_f8f6f4 v[76:79], v[140:143], v[0:3], v[22:25], v187, v187 op_sel_hi:[0,0,0] cbsz:4 blgp:4
	s_waitcnt vmcnt(17)
	v_mfma_scale_f32_16x16x128_f8f6f4 v[22:25], v[144:147], v[4:7], v[34:37], v187, v187 op_sel_hi:[0,0,0] cbsz:4 blgp:4
	s_waitcnt vmcnt(16)
	v_mfma_scale_f32_16x16x128_f8f6f4 v[160:163], v[160:163], v[0:3], v[22:25], v187, v187 op_sel_hi:[0,0,0] cbsz:4 blgp:4
	global_load_dwordx4 v[196:199], v[8:9], off offset:896
	global_load_dwordx4 v[200:203], v[8:9], off offset:960
	global_load_dwordx4 v[204:207], v[10:11], off offset:896
	global_load_dwordx4 v[208:211], v[10:11], off offset:960
	global_load_dwordx4 v[226:229], v[18:19], off offset:896
	global_load_dwordx4 v[230:233], v[18:19], off offset:960
	global_load_dwordx4 v[234:237], v[20:21], off offset:896
	global_load_dwordx4 v[238:241], v[20:21], off offset:960
	s_waitcnt vmcnt(23)
	v_mfma_scale_f32_16x16x128_f8f6f4 v[8:11], v[80:83], v[4:7], v[38:41], v187, v187 op_sel_hi:[0,0,0] cbsz:4 blgp:4
	s_waitcnt vmcnt(22)
	v_mfma_scale_f32_16x16x128_f8f6f4 v[80:83], v[84:87], v[0:3], v[8:11], v187, v187 op_sel_hi:[0,0,0] cbsz:4 blgp:4
	s_waitcnt vmcnt(21)
	v_mfma_scale_f32_16x16x128_f8f6f4 v[8:11], v[88:91], v[4:7], v[42:45], v187, v187 op_sel_hi:[0,0,0] cbsz:4 blgp:4
	s_waitcnt vmcnt(20)
	v_mfma_scale_f32_16x16x128_f8f6f4 v[84:87], v[92:95], v[0:3], v[8:11], v187, v187 op_sel_hi:[0,0,0] cbsz:4 blgp:4
	s_waitcnt vmcnt(19)
	v_mfma_scale_f32_16x16x128_f8f6f4 v[8:11], v[128:131], v[4:7], v[46:49], v187, v187 op_sel_hi:[0,0,0] cbsz:4 blgp:4
	s_waitcnt vmcnt(17)
	v_mfma_scale_f32_16x16x128_f8f6f4 v[4:7], v[164:167], v[4:7], v[56:59], v187, v187 op_sel_hi:[0,0,0] cbsz:4 blgp:4
	v_mfma_scale_f32_16x16x128_f8f6f4 v[88:91], v[132:135], v[0:3], v[8:11], v187, v187 op_sel_hi:[0,0,0] cbsz:4 blgp:4
	s_waitcnt vmcnt(16)
	v_mfma_scale_f32_16x16x128_f8f6f4 v[92:95], v[168:171], v[0:3], v[4:7], v187, v187 op_sel_hi:[0,0,0] cbsz:4 blgp:4
	v_mov_b32_e32 v0, v52
	v_mov_b32_e32 v1, v16
	v_mov_b32_e32 v22, v53
	v_mov_b32_e32 v23, v16
	v_mov_b32_e32 v38, v54
	v_mov_b32_e32 v39, v16
	v_mov_b32_e32 v54, v55
	v_mov_b32_e32 v55, v16
	v_lshlrev_b64 v[0:1], 10, v[0:1]
	v_lshlrev_b64 v[22:23], 10, v[22:23]
	v_lshlrev_b64 v[38:39], 10, v[38:39]
	v_lshlrev_b64 v[54:55], 10, v[54:55]
	v_lshl_add_u64 v[18:19], v[182:183], 0, v[0:1]
	v_lshl_add_u64 v[34:35], v[182:183], 0, v[22:23]
	v_lshl_add_u64 v[50:51], v[182:183], 0, v[38:39]
	v_lshl_add_u64 v[66:67], v[182:183], 0, v[54:55]
	global_load_dwordx4 v[0:3], v[18:19], off
	global_load_dwordx4 v[4:7], v[18:19], off offset:256
	global_load_dwordx4 v[8:11], v[18:19], off offset:512
	s_nop 0
	global_load_dwordx4 v[18:21], v[18:19], off offset:768
	s_nop 0
	global_load_dwordx4 v[22:25], v[34:35], off
	global_load_dwordx4 v[26:29], v[34:35], off offset:256
	global_load_dwordx4 v[30:33], v[34:35], off offset:512
	s_nop 0
	global_load_dwordx4 v[34:37], v[34:35], off offset:768
	s_nop 0
	global_load_dwordx4 v[38:41], v[50:51], off
	global_load_dwordx4 v[42:45], v[50:51], off offset:256
	global_load_dwordx4 v[46:49], v[50:51], off offset:512
	s_nop 0
	global_load_dwordx4 v[50:53], v[50:51], off offset:768
	s_nop 0
	global_load_dwordx4 v[54:57], v[66:67], off
	global_load_dwordx4 v[58:61], v[66:67], off offset:256
	global_load_dwordx4 v[62:65], v[66:67], off offset:512
	s_nop 0
	global_load_dwordx4 v[66:69], v[66:67], off offset:768
	ds_read_b128 v[164:167], v70 offset:960
	ds_read_b128 v[168:171], v70 offset:896
	s_waitcnt vmcnt(29) lgkmcnt(0)
	v_mfma_scale_f32_16x16x128_f8f6f4 v[70:73], v[104:107], v[168:171], v[72:75], v187, v187 op_sel_hi:[0,0,0] cbsz:4 blgp:4
	s_waitcnt vmcnt(28)
	v_mfma_scale_f32_16x16x128_f8f6f4 v[142:145], v[108:111], v[164:167], v[70:73], v187, v187 op_sel_hi:[0,0,0] cbsz:4 blgp:4
	s_waitcnt vmcnt(27)
	v_mfma_scale_f32_16x16x128_f8f6f4 v[70:73], v[112:115], v[168:171], v[76:79], v187, v187 op_sel_hi:[0,0,0] cbsz:4 blgp:4
	v_mfma_scale_f32_16x16x128_f8f6f4 v[96:99], v[96:99], v[168:171], v[172:175], v187, v187 op_sel_hi:[0,0,0] cbsz:4 blgp:4
	s_waitcnt vmcnt(26)
	v_mfma_scale_f32_16x16x128_f8f6f4 v[138:141], v[116:119], v[164:167], v[70:73], v187, v187 op_sel_hi:[0,0,0] cbsz:4 blgp:4
	s_waitcnt vmcnt(25)
	v_mfma_scale_f32_16x16x128_f8f6f4 v[70:73], v[120:123], v[168:171], v[160:163], v187, v187 op_sel_hi:[0,0,0] cbsz:4 blgp:4
	v_mfma_scale_f32_16x16x128_f8f6f4 v[146:149], v[100:103], v[164:167], v[96:99], v187, v187 op_sel_hi:[0,0,0] cbsz:4 blgp:4
	s_waitcnt vmcnt(24)
	v_mfma_scale_f32_16x16x128_f8f6f4 v[134:137], v[124:127], v[164:167], v[70:73], v187, v187 op_sel_hi:[0,0,0] cbsz:4 blgp:4
	s_waitcnt vmcnt(23)
	v_mfma_scale_f32_16x16x128_f8f6f4 v[70:73], v[196:199], v[168:171], v[80:83], v187, v187 op_sel_hi:[0,0,0] cbsz:4 blgp:4
	s_waitcnt vmcnt(22)
	v_mfma_scale_f32_16x16x128_f8f6f4 v[130:133], v[200:203], v[164:167], v[70:73], v187, v187 op_sel_hi:[0,0,0] cbsz:4 blgp:4
	s_waitcnt vmcnt(21)
	v_mfma_scale_f32_16x16x128_f8f6f4 v[70:73], v[204:207], v[168:171], v[84:87], v187, v187 op_sel_hi:[0,0,0] cbsz:4 blgp:4
	s_waitcnt vmcnt(20)
	v_mfma_scale_f32_16x16x128_f8f6f4 v[126:129], v[208:211], v[164:167], v[70:73], v187, v187 op_sel_hi:[0,0,0] cbsz:4 blgp:4
	s_waitcnt vmcnt(19)
	v_mfma_scale_f32_16x16x128_f8f6f4 v[70:73], v[226:229], v[168:171], v[88:91], v187, v187 op_sel_hi:[0,0,0] cbsz:4 blgp:4
	s_waitcnt vmcnt(18)
	v_mfma_scale_f32_16x16x128_f8f6f4 v[122:125], v[230:233], v[164:167], v[70:73], v187, v187 op_sel_hi:[0,0,0] cbsz:4 blgp:4
	s_waitcnt vmcnt(17)
	v_mfma_scale_f32_16x16x128_f8f6f4 v[70:73], v[234:237], v[168:171], v[92:95], v187, v187 op_sel_hi:[0,0,0] cbsz:4 blgp:4
	s_waitcnt vmcnt(16)
	v_mfma_scale_f32_16x16x128_f8f6f4 v[118:121], v[238:241], v[164:167], v[70:73], v187, v187 op_sel_hi:[0,0,0] cbsz:4 blgp:4
	s_nop 5
	v_mov_b32_e32 v70, v12
	v_mov_b32_e32 v71, v16
	v_mov_b32_e32 v12, v13
	v_mov_b32_e32 v13, v16
	v_lshlrev_b64 v[70:71], 10, v[70:71]
	v_lshlrev_b64 v[12:13], 10, v[12:13]
	v_lshl_add_u64 v[82:83], v[182:183], 0, v[70:71]
	v_lshl_add_u64 v[12:13], v[182:183], 0, v[12:13]
	global_load_dwordx4 v[70:73], v[82:83], off
	global_load_dwordx4 v[74:77], v[82:83], off offset:256
	global_load_dwordx4 v[78:81], v[82:83], off offset:512
	s_nop 0
	global_load_dwordx4 v[82:85], v[82:83], off offset:768
	s_nop 0
	global_load_dwordx4 v[86:89], v[12:13], off
	global_load_dwordx4 v[90:93], v[12:13], off offset:256
	global_load_dwordx4 v[94:97], v[12:13], off offset:512
	global_load_dwordx4 v[98:101], v[12:13], off offset:768
	v_mov_b32_e32 v12, v14
	v_mov_b32_e32 v13, v16
	v_lshlrev_b64 v[12:13], 10, v[12:13]
	v_lshl_add_u64 v[12:13], v[182:183], 0, v[12:13]
	global_load_dwordx4 v[102:105], v[12:13], off
	global_load_dwordx4 v[106:109], v[12:13], off offset:256
	global_load_dwordx4 v[110:113], v[12:13], off offset:512
	global_load_dwordx4 v[114:117], v[12:13], off offset:768
	v_cmp_lt_i32_e32 vcc, 0, v154
	v_mov_b32_e32 v12, 0x3d321643
	s_and_saveexec_b64 s[10:11], vcc
	s_cbranch_execz .LBB0_738
	v_cmp_ne_u32_e32 vcc, 1, v154
	s_and_saveexec_b64 s[12:13], vcc
	s_xor_b64 s[12:13], exec, s[12:13]
	v_cmp_eq_u32_e32 vcc, 2, v154
	v_mov_b32_e32 v12, 0x3a321643
	v_mov_b32_e32 v13, 0x3b321643
	v_cndmask_b32_e32 v12, v12, v13, vcc
	s_andn2_saveexec_b64 s[12:13], s[12:13]
	v_mov_b32_e32 v12, 0x3c321643
	s_or_b64 exec, exec, s[12:13]

.LBB0_778:
	s_lshl_b32 s99, s61, 12
	v_lshl_add_u32 v242, v214, 6, s99
	v_mov_b32_e32 v243, 0
	v_lshl_add_u64 v[244:245], v[178:179], 0, v[242:243]
	s_lshl_b32 s98, s90, 12
	s_add_i32 s98, s98, 0x1b000
	s_mov_b32 m0, s98
	s_nop 0
	global_load_lds_dwordx4 v[244:245], off
	s_add_i32 m0, s98, 1008
	s_nop 0
	global_load_lds_dwordx4 v[244:245], off offset:16
	s_add_i32 m0, s98, 2016
	s_nop 0
	global_load_lds_dwordx4 v[244:245], off offset:32
	s_add_i32 m0, s98, 3024
	s_nop 0
	global_load_lds_dwordx4 v[244:245], off offset:48
	s_mov_b32 s100, 1
	v_cmp_gt_i32_e64 s[10:11], s85, v180
	v_cmp_lt_i32_e64 s[12:13], s93, v180
	s_mov_b64 s[38:39], -1
	s_and_b64 vcc, exec, s[44:45]
	v_lshlrev_b64 v[2:3], 13, v[180:181]
	s_cbranch_vccz .LBB0_780
	v_lshlrev_b64 v[0:1], 13, v[180:181]
	v_lshl_add_u64 v[4:5], s[36:37], 0, v[0:1]
	v_lshl_add_u64 v[38:39], v[4:5], 0, s[96:97]
	s_mov_b64 s[38:39], 0
